# hoist ssq loads in EpiScale/EpiFfn epilogues; 3-deep prefetch ring for residual loads in EpiRes epilogues (out-proj L0/L1, FFN-down L0)
# speedup vs baseline: 1.0030x; 1.0030x over previous
; __device__ __forceinline__ unsigned cvt_pk_bf16(float lo, float hi) { f32x2_t v = {lo, hi}; bf16x2_t b = __builtin_convertvector(v, bf16x2_t); return __builtin_bit_cast(unsigned, b); }
;     __device__ __forceinline__ void operator()(f32x4 (&acc)[2][2][4][2], const Unit& u, int wr, int wc, int fr, int fq) const {
;     ...
;         for (int ai = 0; ai < 2; ++ai)
; #pragma unroll
;             for (int m = 0; m < 4; ++m) {
;                 const int g = u.pm * BM + ai * HALF + wr * 64 + m * 16 + fr; const bool ok = g < M;
;                 const float rs = ok ? rsqrtf(ssq[g] * (1.0f / DM) + EPS) : 0.f;
;                 bf16_t* rowp = O + (size_t)g * ldc + u.pn * BM + wc * 32 + 8 * fq;
; #pragma unroll
;                 for (int bj = 0; bj < 2; ++bj) {
;                     f32x4 v0 = acc[ai][bj][m][0], v1 = acc[ai][bj][m][1]; u32x4 w;
;                     if (ok) { w.x = cvt_pk_bf16(v0[0] * rs, v0[1] * rs); w.y = cvt_pk_bf16(v0[2] * rs, v0[3] * rs); w.z = cvt_pk_bf16(v1[0] * rs, v1[1] * rs); w.w = cvt_pk_bf16(v1[2] * rs, v1[3] * rs); }
;                     else { w = (u32x4){0u, 0u, 0u, 0u}; }
;                     *(u32x4*)(rowp + bj * HALF) = w;
.LBB0_275:
	v_lshl_add_u32 v154, s0, 8, v157
	v_mov_b32_e32 v164, v154
	v_mov_b32_e32 v165, 0
	v_lshl_add_u64 v[164:165], v[164:165], 2, s[34:35]
	global_load_dword v166, v[164:165], off
	global_load_dword v167, v[164:165], off offset:64
	global_load_dword v168, v[164:165], off offset:128
	global_load_dword v169, v[164:165], off offset:192
	global_load_dword v170, v[164:165], off offset:512
	global_load_dword v171, v[164:165], off offset:576
	global_load_dword v172, v[164:165], off offset:640
	global_load_dword v173, v[164:165], off offset:704
	s_waitcnt vmcnt(0)
	v_cmp_gt_i32_e32 vcc, s44, v154
	v_cmp_lt_i32_e64 s[0:1], s45, v154
	s_and_saveexec_b64 s[22:23], s[0:1]
	s_xor_b64 s[0:1], exec, s[22:23]
	v_mov_b32_e32 v155, v145
	s_or_saveexec_b64 s[22:23], s[0:1]
	v_mov_b32_e32 v128, 0
	v_mov_b32_e32 v156, 0
	s_xor_b64 exec, exec, s[22:23]
	s_cbranch_execz .LBB0_279
	v_ashrrev_i32_e32 v155, 31, v154
	v_lshl_add_u64 v[130:131], v[154:155], 2, s[34:35]
	v_mov_b32_e32 v129, v166
	v_fmamk_f32 v129, v129, 0x3a000000, v162
	v_mul_f32_e32 v130, 0x4b800000, v129
	v_cmp_gt_f32_e64 s[0:1], s46, v129
	s_nop 1
	v_cndmask_b32_e64 v129, v129, v130, s[0:1]
	v_rsq_f32_e32 v129, v129
	s_nop 0
	v_mul_f32_e32 v130, 0x45800000, v129
	v_cndmask_b32_e64 v156, v129, v130, s[0:1]

; __device__ __forceinline__ unsigned cvt_pk_bf16(float lo, float hi) { f32x2_t v = {lo, hi}; bf16x2_t b = __builtin_convertvector(v, bf16x2_t); return __builtin_bit_cast(unsigned, b); }
;     __device__ __forceinline__ void operator()(f32x4 (&acc)[2][2][4][2], const Unit& u, int wr, int wc, int fr, int fq) const {
;     ...
;             for (int m = 0; m < 4; ++m) {
;                 const int g = u.pm * BM + ai * HALF + wr * 64 + m * 16 + fr; const bool ok = g < M;
;                 const float rs = ok ? rsqrtf(ssq[g] * (1.0f / DM) + EPS) : 0.f;
;                 bf16_t* rowp = O + (size_t)g * ldc + u.pn * BM + wc * 32 + 8 * fq;
; #pragma unroll
;                 for (int bj = 0; bj < 2; ++bj) {
;                     f32x4 v0 = acc[ai][bj][m][0], v1 = acc[ai][bj][m][1]; u32x4 w;
;                     if (ok) { w.x = cvt_pk_bf16(v0[0] * rs, v0[1] * rs); w.y = cvt_pk_bf16(v0[2] * rs, v0[3] * rs); w.z = cvt_pk_bf16(v1[0] * rs, v1[1] * rs); w.w = cvt_pk_bf16(v1[2] * rs, v1[3] * rs); }
;                     else { w = (u32x4){0u, 0u, 0u, 0u}; }
;                     *(u32x4*)(rowp + bj * HALF) = w;
.LBB0_281:
	s_or_b64 exec, exec, s[0:1]
	v_mov_b64_e32 v[112:113], s[70:71]
	v_mad_u64_u32 v[112:113], s[0:1], v154, s47, v[112:113]
	v_mov_b32_e32 v114, v113
	s_lshl_b32 s20, s20, 8
	v_mad_u64_u32 v[114:115], s[0:1], v155, s47, v[114:115]
	s_ashr_i32 s21, s20, 31
	v_mov_b32_e32 v113, v114
	v_lshl_add_u64 v[112:113], s[20:21], 1, v[112:113]
	v_lshl_add_u64 v[112:113], v[112:113], 0, s[4:5]
	v_or_b32_e32 v120, 16, v154
	v_lshl_add_u64 v[112:113], v[112:113], 0, v[144:145]
	v_cmp_gt_i32_e32 vcc, s44, v120
	v_cmp_lt_i32_e64 s[0:1], s45, v120
	global_store_dwordx4 v[112:113], v[128:131], off
	global_store_dwordx4 v[112:113], v[132:135], off offset:256
	s_and_saveexec_b64 s[22:23], s[0:1]
	s_xor_b64 s[0:1], exec, s[22:23]
	v_mov_b32_e32 v121, v145
	s_or_saveexec_b64 s[22:23], s[0:1]
	v_mov_b32_e32 v112, 0
	v_mov_b32_e32 v122, 0
	s_xor_b64 exec, exec, s[22:23]
	s_cbranch_execz .LBB0_285
	v_ashrrev_i32_e32 v121, 31, v120
	v_lshl_add_u64 v[114:115], v[120:121], 2, s[34:35]
	v_mov_b32_e32 v113, v167
	v_fmamk_f32 v113, v113, 0x3a000000, v162
	v_mul_f32_e32 v114, 0x4b800000, v113
	v_cmp_gt_f32_e64 s[0:1], s46, v113
	s_nop 1
	v_cndmask_b32_e64 v113, v113, v114, s[0:1]
	v_rsq_f32_e32 v113, v113
	s_nop 0
	v_mul_f32_e32 v114, 0x45800000, v113
	v_cndmask_b32_e64 v122, v113, v114, s[0:1]

; __device__ __forceinline__ unsigned cvt_pk_bf16(float lo, float hi) { f32x2_t v = {lo, hi}; bf16x2_t b = __builtin_convertvector(v, bf16x2_t); return __builtin_bit_cast(unsigned, b); }
;     __device__ __forceinline__ void operator()(f32x4 (&acc)[2][2][4][2], const Unit& u, int wr, int wc, int fr, int fq) const {
;     ...
;             for (int m = 0; m < 4; ++m) {
;                 const int g = u.pm * BM + ai * HALF + wr * 64 + m * 16 + fr; const bool ok = g < M;
;                 const float rs = ok ? rsqrtf(ssq[g] * (1.0f / DM) + EPS) : 0.f;
;                 bf16_t* rowp = O + (size_t)g * ldc + u.pn * BM + wc * 32 + 8 * fq;
; #pragma unroll
;                 for (int bj = 0; bj < 2; ++bj) {
;                     f32x4 v0 = acc[ai][bj][m][0], v1 = acc[ai][bj][m][1]; u32x4 w;
;                     if (ok) { w.x = cvt_pk_bf16(v0[0] * rs, v0[1] * rs); w.y = cvt_pk_bf16(v0[2] * rs, v0[3] * rs); w.z = cvt_pk_bf16(v1[0] * rs, v1[1] * rs); w.w = cvt_pk_bf16(v1[2] * rs, v1[3] * rs); }
;                     else { w = (u32x4){0u, 0u, 0u, 0u}; }
;                     *(u32x4*)(rowp + bj * HALF) = w;
.LBB0_287:
	s_or_b64 exec, exec, s[0:1]
	v_mov_b64_e32 v[96:97], s[70:71]
	v_mad_u64_u32 v[96:97], s[0:1], v120, s47, v[96:97]
	v_mov_b32_e32 v98, v97
	v_mad_u64_u32 v[98:99], s[0:1], v121, s47, v[98:99]
	v_mov_b32_e32 v97, v98
	v_lshl_add_u64 v[96:97], s[20:21], 1, v[96:97]
	v_lshl_add_u64 v[96:97], v[96:97], 0, s[4:5]
	v_or_b32_e32 v104, 32, v154
	v_lshl_add_u64 v[96:97], v[96:97], 0, v[144:145]
	v_cmp_gt_i32_e32 vcc, s44, v104
	v_cmp_lt_i32_e64 s[0:1], s45, v104
	global_store_dwordx4 v[96:97], v[112:115], off
	global_store_dwordx4 v[96:97], v[116:119], off offset:256
	s_and_saveexec_b64 s[22:23], s[0:1]
	s_xor_b64 s[0:1], exec, s[22:23]
	v_mov_b32_e32 v105, v145
	s_or_saveexec_b64 s[22:23], s[0:1]
	v_mov_b32_e32 v96, 0
	v_mov_b32_e32 v106, 0
	s_xor_b64 exec, exec, s[22:23]
	s_cbranch_execz .LBB0_291
	v_ashrrev_i32_e32 v105, 31, v104
	v_lshl_add_u64 v[98:99], v[104:105], 2, s[34:35]
	v_mov_b32_e32 v97, v168
	v_fmamk_f32 v97, v97, 0x3a000000, v162
	v_mul_f32_e32 v98, 0x4b800000, v97
	v_cmp_gt_f32_e64 s[0:1], s46, v97
	s_nop 1
	v_cndmask_b32_e64 v97, v97, v98, s[0:1]
	v_rsq_f32_e32 v97, v97
	s_nop 0
	v_mul_f32_e32 v98, 0x45800000, v97
	v_cndmask_b32_e64 v106, v97, v98, s[0:1]

; __device__ __forceinline__ unsigned cvt_pk_bf16(float lo, float hi) { f32x2_t v = {lo, hi}; bf16x2_t b = __builtin_convertvector(v, bf16x2_t); return __builtin_bit_cast(unsigned, b); }
;     __device__ __forceinline__ void operator()(f32x4 (&acc)[2][2][4][2], const Unit& u, int wr, int wc, int fr, int fq) const {
;     ...
;             for (int m = 0; m < 4; ++m) {
;                 const int g = u.pm * BM + ai * HALF + wr * 64 + m * 16 + fr; const bool ok = g < M;
;                 const float rs = ok ? rsqrtf(ssq[g] * (1.0f / DM) + EPS) : 0.f;
;                 bf16_t* rowp = O + (size_t)g * ldc + u.pn * BM + wc * 32 + 8 * fq;
; #pragma unroll
;                 for (int bj = 0; bj < 2; ++bj) {
;                     f32x4 v0 = acc[ai][bj][m][0], v1 = acc[ai][bj][m][1]; u32x4 w;
;                     if (ok) { w.x = cvt_pk_bf16(v0[0] * rs, v0[1] * rs); w.y = cvt_pk_bf16(v0[2] * rs, v0[3] * rs); w.z = cvt_pk_bf16(v1[0] * rs, v1[1] * rs); w.w = cvt_pk_bf16(v1[2] * rs, v1[3] * rs); }
;                     else { w = (u32x4){0u, 0u, 0u, 0u}; }
;                     *(u32x4*)(rowp + bj * HALF) = w;
.LBB0_293:
	s_or_b64 exec, exec, s[0:1]
	v_mov_b64_e32 v[80:81], s[70:71]
	v_mad_u64_u32 v[80:81], s[0:1], v104, s47, v[80:81]
	v_mov_b32_e32 v82, v81
	v_mad_u64_u32 v[82:83], s[0:1], v105, s47, v[82:83]
	v_mov_b32_e32 v81, v82
	v_lshl_add_u64 v[80:81], s[20:21], 1, v[80:81]
	v_lshl_add_u64 v[80:81], v[80:81], 0, s[4:5]
	v_or_b32_e32 v88, 48, v154
	v_lshl_add_u64 v[80:81], v[80:81], 0, v[144:145]
	v_cmp_gt_i32_e32 vcc, s44, v88
	v_cmp_lt_i32_e64 s[0:1], s45, v88
	global_store_dwordx4 v[80:81], v[96:99], off
	global_store_dwordx4 v[80:81], v[100:103], off offset:256
	s_and_saveexec_b64 s[22:23], s[0:1]
	s_xor_b64 s[0:1], exec, s[22:23]
	v_mov_b32_e32 v89, v145
	s_or_saveexec_b64 s[22:23], s[0:1]
	v_mov_b32_e32 v80, 0
	v_mov_b32_e32 v90, 0
	s_xor_b64 exec, exec, s[22:23]
	s_cbranch_execz .LBB0_297
	v_ashrrev_i32_e32 v89, 31, v88
	v_lshl_add_u64 v[82:83], v[88:89], 2, s[34:35]
	v_mov_b32_e32 v81, v169
	v_fmamk_f32 v81, v81, 0x3a000000, v162
	v_mul_f32_e32 v82, 0x4b800000, v81
	v_cmp_gt_f32_e64 s[0:1], s46, v81
	s_nop 1
	v_cndmask_b32_e64 v81, v81, v82, s[0:1]
	v_rsq_f32_e32 v81, v81
	s_nop 0
	v_mul_f32_e32 v82, 0x45800000, v81
	v_cndmask_b32_e64 v90, v81, v82, s[0:1]

; __device__ __forceinline__ unsigned cvt_pk_bf16(float lo, float hi) { f32x2_t v = {lo, hi}; bf16x2_t b = __builtin_convertvector(v, bf16x2_t); return __builtin_bit_cast(unsigned, b); }
;     __device__ __forceinline__ void operator()(f32x4 (&acc)[2][2][4][2], const Unit& u, int wr, int wc, int fr, int fq) const {
;     ...
;             for (int m = 0; m < 4; ++m) {
;                 const int g = u.pm * BM + ai * HALF + wr * 64 + m * 16 + fr; const bool ok = g < M;
;                 const float rs = ok ? rsqrtf(ssq[g] * (1.0f / DM) + EPS) : 0.f;
;                 bf16_t* rowp = O + (size_t)g * ldc + u.pn * BM + wc * 32 + 8 * fq;
; #pragma unroll
;                 for (int bj = 0; bj < 2; ++bj) {
;                     f32x4 v0 = acc[ai][bj][m][0], v1 = acc[ai][bj][m][1]; u32x4 w;
;                     if (ok) { w.x = cvt_pk_bf16(v0[0] * rs, v0[1] * rs); w.y = cvt_pk_bf16(v0[2] * rs, v0[3] * rs); w.z = cvt_pk_bf16(v1[0] * rs, v1[1] * rs); w.w = cvt_pk_bf16(v1[2] * rs, v1[3] * rs); }
;                     else { w = (u32x4){0u, 0u, 0u, 0u}; }
;                     *(u32x4*)(rowp + bj * HALF) = w;
.LBB0_299:
	s_or_b64 exec, exec, s[0:1]
	v_mov_b64_e32 v[64:65], s[70:71]
	v_mad_u64_u32 v[64:65], s[0:1], v88, s47, v[64:65]
	v_mov_b32_e32 v66, v65
	v_mad_u64_u32 v[66:67], s[0:1], v89, s47, v[66:67]
	v_mov_b32_e32 v65, v66
	v_lshl_add_u64 v[64:65], s[20:21], 1, v[64:65]
	v_lshl_add_u64 v[64:65], v[64:65], 0, s[4:5]
	v_add_u32_e32 v72, 0x80, v154
	v_lshl_add_u64 v[64:65], v[64:65], 0, v[144:145]
	v_cmp_gt_i32_e32 vcc, s44, v72
	v_cmp_lt_i32_e64 s[0:1], s45, v72
	global_store_dwordx4 v[64:65], v[80:83], off
	global_store_dwordx4 v[64:65], v[84:87], off offset:256
	s_and_saveexec_b64 s[22:23], s[0:1]
	s_xor_b64 s[0:1], exec, s[22:23]
	v_mov_b32_e32 v73, v145
	s_or_saveexec_b64 s[22:23], s[0:1]
	v_mov_b32_e32 v64, 0
	v_mov_b32_e32 v74, 0
	s_xor_b64 exec, exec, s[22:23]
	s_cbranch_execz .LBB0_303
	v_ashrrev_i32_e32 v73, 31, v72
	v_lshl_add_u64 v[66:67], v[72:73], 2, s[34:35]
	v_mov_b32_e32 v65, v170
	v_fmamk_f32 v65, v65, 0x3a000000, v162
	v_mul_f32_e32 v66, 0x4b800000, v65
	v_cmp_gt_f32_e64 s[0:1], s46, v65
	s_nop 1
	v_cndmask_b32_e64 v65, v65, v66, s[0:1]
	v_rsq_f32_e32 v65, v65
	s_nop 0
	v_mul_f32_e32 v66, 0x45800000, v65
	v_cndmask_b32_e64 v74, v65, v66, s[0:1]

; __device__ __forceinline__ unsigned cvt_pk_bf16(float lo, float hi) { f32x2_t v = {lo, hi}; bf16x2_t b = __builtin_convertvector(v, bf16x2_t); return __builtin_bit_cast(unsigned, b); }
;     __device__ __forceinline__ void operator()(f32x4 (&acc)[2][2][4][2], const Unit& u, int wr, int wc, int fr, int fq) const {
;     ...
;             for (int m = 0; m < 4; ++m) {
;                 const int g = u.pm * BM + ai * HALF + wr * 64 + m * 16 + fr; const bool ok = g < M;
;                 const float rs = ok ? rsqrtf(ssq[g] * (1.0f / DM) + EPS) : 0.f;
;                 bf16_t* rowp = O + (size_t)g * ldc + u.pn * BM + wc * 32 + 8 * fq;
; #pragma unroll
;                 for (int bj = 0; bj < 2; ++bj) {
;                     f32x4 v0 = acc[ai][bj][m][0], v1 = acc[ai][bj][m][1]; u32x4 w;
;                     if (ok) { w.x = cvt_pk_bf16(v0[0] * rs, v0[1] * rs); w.y = cvt_pk_bf16(v0[2] * rs, v0[3] * rs); w.z = cvt_pk_bf16(v1[0] * rs, v1[1] * rs); w.w = cvt_pk_bf16(v1[2] * rs, v1[3] * rs); }
;                     else { w = (u32x4){0u, 0u, 0u, 0u}; }
;                     *(u32x4*)(rowp + bj * HALF) = w;
.LBB0_305:
	s_or_b64 exec, exec, s[0:1]
	v_mov_b64_e32 v[48:49], s[70:71]
	v_mad_u64_u32 v[48:49], s[0:1], v72, s47, v[48:49]
	v_mov_b32_e32 v50, v49
	v_mad_u64_u32 v[50:51], s[0:1], v73, s47, v[50:51]
	v_mov_b32_e32 v49, v50
	v_lshl_add_u64 v[48:49], s[20:21], 1, v[48:49]
	v_lshl_add_u64 v[48:49], v[48:49], 0, s[4:5]
	v_add_u32_e32 v56, 0x90, v154
	v_lshl_add_u64 v[48:49], v[48:49], 0, v[144:145]
	v_cmp_gt_i32_e32 vcc, s44, v56
	v_cmp_lt_i32_e64 s[0:1], s45, v56
	global_store_dwordx4 v[48:49], v[64:67], off
	global_store_dwordx4 v[48:49], v[68:71], off offset:256
	s_and_saveexec_b64 s[22:23], s[0:1]
	s_xor_b64 s[0:1], exec, s[22:23]
	v_mov_b32_e32 v57, v145
	s_or_saveexec_b64 s[22:23], s[0:1]
	v_mov_b32_e32 v48, 0
	v_mov_b32_e32 v58, 0
	s_xor_b64 exec, exec, s[22:23]
	s_cbranch_execz .LBB0_309
	v_ashrrev_i32_e32 v57, 31, v56
	v_lshl_add_u64 v[50:51], v[56:57], 2, s[34:35]
	v_mov_b32_e32 v49, v171
	v_fmamk_f32 v49, v49, 0x3a000000, v162
	v_mul_f32_e32 v50, 0x4b800000, v49
	v_cmp_gt_f32_e64 s[0:1], s46, v49
	s_nop 1
	v_cndmask_b32_e64 v49, v49, v50, s[0:1]
	v_rsq_f32_e32 v49, v49
	s_nop 0
	v_mul_f32_e32 v50, 0x45800000, v49
	v_cndmask_b32_e64 v58, v49, v50, s[0:1]

; __device__ __forceinline__ unsigned cvt_pk_bf16(float lo, float hi) { f32x2_t v = {lo, hi}; bf16x2_t b = __builtin_convertvector(v, bf16x2_t); return __builtin_bit_cast(unsigned, b); }
;     __device__ __forceinline__ void operator()(f32x4 (&acc)[2][2][4][2], const Unit& u, int wr, int wc, int fr, int fq) const {
;     ...
;             for (int m = 0; m < 4; ++m) {
;                 const int g = u.pm * BM + ai * HALF + wr * 64 + m * 16 + fr; const bool ok = g < M;
;                 const float rs = ok ? rsqrtf(ssq[g] * (1.0f / DM) + EPS) : 0.f;
;                 bf16_t* rowp = O + (size_t)g * ldc + u.pn * BM + wc * 32 + 8 * fq;
; #pragma unroll
;                 for (int bj = 0; bj < 2; ++bj) {
;                     f32x4 v0 = acc[ai][bj][m][0], v1 = acc[ai][bj][m][1]; u32x4 w;
;                     if (ok) { w.x = cvt_pk_bf16(v0[0] * rs, v0[1] * rs); w.y = cvt_pk_bf16(v0[2] * rs, v0[3] * rs); w.z = cvt_pk_bf16(v1[0] * rs, v1[1] * rs); w.w = cvt_pk_bf16(v1[2] * rs, v1[3] * rs); }
;                     else { w = (u32x4){0u, 0u, 0u, 0u}; }
;                     *(u32x4*)(rowp + bj * HALF) = w;
.LBB0_311:
	s_or_b64 exec, exec, s[0:1]
	v_mov_b64_e32 v[32:33], s[70:71]
	v_mad_u64_u32 v[32:33], s[0:1], v56, s47, v[32:33]
	v_mov_b32_e32 v34, v33
	v_mad_u64_u32 v[34:35], s[0:1], v57, s47, v[34:35]
	v_mov_b32_e32 v33, v34
	v_lshl_add_u64 v[32:33], s[20:21], 1, v[32:33]
	v_lshl_add_u64 v[32:33], v[32:33], 0, s[4:5]
	v_add_u32_e32 v40, 0xa0, v154
	v_lshl_add_u64 v[32:33], v[32:33], 0, v[144:145]
	v_cmp_gt_i32_e32 vcc, s44, v40
	v_cmp_lt_i32_e64 s[0:1], s45, v40
	global_store_dwordx4 v[32:33], v[48:51], off
	global_store_dwordx4 v[32:33], v[52:55], off offset:256
	s_and_saveexec_b64 s[22:23], s[0:1]
	s_xor_b64 s[0:1], exec, s[22:23]
	v_mov_b32_e32 v41, v145
	s_or_saveexec_b64 s[22:23], s[0:1]
	v_mov_b32_e32 v32, 0
	v_mov_b32_e32 v42, 0
	s_xor_b64 exec, exec, s[22:23]
	s_cbranch_execz .LBB0_315
	v_ashrrev_i32_e32 v41, 31, v40
	v_lshl_add_u64 v[34:35], v[40:41], 2, s[34:35]
	v_mov_b32_e32 v33, v172
	v_fmamk_f32 v33, v33, 0x3a000000, v162
	v_mul_f32_e32 v34, 0x4b800000, v33
	v_cmp_gt_f32_e64 s[0:1], s46, v33
	s_nop 1
	v_cndmask_b32_e64 v33, v33, v34, s[0:1]
	v_rsq_f32_e32 v33, v33
	s_nop 0
	v_mul_f32_e32 v34, 0x45800000, v33
	v_cndmask_b32_e64 v42, v33, v34, s[0:1]

; __device__ __forceinline__ unsigned cvt_pk_bf16(float lo, float hi) { f32x2_t v = {lo, hi}; bf16x2_t b = __builtin_convertvector(v, bf16x2_t); return __builtin_bit_cast(unsigned, b); }
;     __device__ __forceinline__ void operator()(f32x4 (&acc)[2][2][4][2], const Unit& u, int wr, int wc, int fr, int fq) const {
;     ...
;             for (int m = 0; m < 4; ++m) {
;                 const int g = u.pm * BM + ai * HALF + wr * 64 + m * 16 + fr; const bool ok = g < M;
;                 const float rs = ok ? rsqrtf(ssq[g] * (1.0f / DM) + EPS) : 0.f;
;                 bf16_t* rowp = O + (size_t)g * ldc + u.pn * BM + wc * 32 + 8 * fq;
; #pragma unroll
;                 for (int bj = 0; bj < 2; ++bj) {
;                     f32x4 v0 = acc[ai][bj][m][0], v1 = acc[ai][bj][m][1]; u32x4 w;
;                     if (ok) { w.x = cvt_pk_bf16(v0[0] * rs, v0[1] * rs); w.y = cvt_pk_bf16(v0[2] * rs, v0[3] * rs); w.z = cvt_pk_bf16(v1[0] * rs, v1[1] * rs); w.w = cvt_pk_bf16(v1[2] * rs, v1[3] * rs); }
;                     else { w = (u32x4){0u, 0u, 0u, 0u}; }
;                     *(u32x4*)(rowp + bj * HALF) = w;
.LBB0_317:
	s_or_b64 exec, exec, s[0:1]
	v_mov_b64_e32 v[16:17], s[70:71]
	v_mad_u64_u32 v[16:17], s[0:1], v40, s47, v[16:17]
	v_mov_b32_e32 v18, v17
	v_mad_u64_u32 v[18:19], s[0:1], v41, s47, v[18:19]
	v_mov_b32_e32 v17, v18
	v_lshl_add_u64 v[16:17], s[20:21], 1, v[16:17]
	v_lshl_add_u64 v[16:17], v[16:17], 0, s[4:5]
	v_add_u32_e32 v24, 0xb0, v154
	v_lshl_add_u64 v[16:17], v[16:17], 0, v[144:145]
	v_cmp_gt_i32_e32 vcc, s44, v24
	v_cmp_lt_i32_e64 s[0:1], s45, v24
	global_store_dwordx4 v[16:17], v[32:35], off
	global_store_dwordx4 v[16:17], v[36:39], off offset:256
	s_and_saveexec_b64 s[22:23], s[0:1]
	s_xor_b64 s[0:1], exec, s[22:23]
	v_mov_b32_e32 v25, v145
	s_or_saveexec_b64 s[22:23], s[0:1]
	v_mov_b32_e32 v16, 0
	v_mov_b32_e32 v26, 0
	s_xor_b64 exec, exec, s[22:23]
	s_cbranch_execz .LBB0_321
	v_ashrrev_i32_e32 v25, 31, v24
	v_lshl_add_u64 v[18:19], v[24:25], 2, s[34:35]
	v_mov_b32_e32 v17, v173
	v_fmamk_f32 v17, v17, 0x3a000000, v162
	v_mul_f32_e32 v18, 0x4b800000, v17
	v_cmp_gt_f32_e64 s[0:1], s46, v17
	s_nop 1
	v_cndmask_b32_e64 v17, v17, v18, s[0:1]
	v_rsq_f32_e32 v17, v17
	s_nop 0
	v_mul_f32_e32 v18, 0x45800000, v17
	v_cndmask_b32_e64 v26, v17, v18, s[0:1]

; __device__ __forceinline__ unsigned cvt_pk_bf16(float lo, float hi) { f32x2_t v = {lo, hi}; bf16x2_t b = __builtin_convertvector(v, bf16x2_t); return __builtin_bit_cast(unsigned, b); }
;     __device__ __forceinline__ void operator()(f32x4 (&acc)[2][2][4][2], const Unit& u, int wr, int wc, int fr, int fq) const {
;     ...
;         for (int ai = 0; ai < 2; ++ai)
; #pragma unroll
;             for (int m = 0; m < 4; ++m) {
;                 const int g = u.pm * BM + ai * HALF + wr * 64 + m * 16 + fr; float ss = 0.f;
;                 if (g < M) {
;                     const int b = g >= T ? 1 : 0, t = g - b * T;
;                     const float* sp = t < 16 ? srcm + (size_t)(b * 16 + t) * DM : srcx + ((size_t)b * SEQ + (t - 16)) * DM;
;                     float* dp = t < 16 ? (dstm ? dstm + (size_t)(b * 16 + t) * DM : (float*)nullptr) : dstx + ((size_t)b * SEQ + (t - 16)) * DM;
;                     const int col0 = u.pn * BM + wc * 32 + 8 * fq;
; #pragma unroll
;                     for (int bj = 0; bj < 2; ++bj) {
;                         const int col = col0 + bj * HALF;
;                         const f32x4 v0 = *(const f32x4*)(sp + col) + acc[ai][bj][m][0], v1 = *(const f32x4*)(sp + col + 4) + acc[ai][bj][m][1];
;                         if (dp) { *(f32x4*)(dp + col) = v0; *(f32x4*)(dp + col + 4) = v1; }
;                         if (hb) { u32x4 w; w.x = cvt_pk_bf16(v0[0], v0[1]); w.y = cvt_pk_bf16(v0[2], v0[3]); w.z = cvt_pk_bf16(v1[0], v1[1]); w.w = cvt_pk_bf16(v1[2], v1[3]); *(u32x4*)(hb + (size_t)g * DM + col) = w; }
;                         ss += (v0[0] * v0[0] + v0[1] * v0[1]) + (v0[2] * v0[2] + v0[3] * v0[3]) + (v1[0] * v1[0] + v1[1] * v1[1]) + (v1[2] * v1[2] + v1[3] * v1[3]);
.LBB0_920:
	v_lshl_add_u32 v148, s0, 8, v160
	v_lshl_or_b32 v146, s8, 8, v162
	v_cmp_gt_i32_e32 vcc, s51, v148
	v_mov_b32_e32 v136, 0
	s_and_saveexec_b64 s[28:29], vcc
	s_cbranch_execz .LBB0_934
	v_mov_b32_e32 v226, v146
	v_mov_b32_e32 v227, 0
	v_mov_b32_e32 v220, v148
	v_add_u32_e32 v221, 0x3ff0, v220
	v_lshrrev_b32_e32 v221, 15, v221
	v_mul_u32_u24_e32 v224, 0x4010, v221
	v_sub_u32_e32 v224, v220, v224
	v_lshlrev_b32_e32 v225, 4, v221
	v_cmp_gt_u32_e64 s[8:9], 16, v224
	v_add_u32_e32 v224, v224, v225
	v_sub_u32_e32 v220, v220, v225
	v_subrev_u32_e32 v220, 16, v220
	v_mov_b32_e32 v222, s68
	v_mov_b32_e32 v223, s69
	v_cndmask_b32_e64 v220, v220, v224, s[8:9]
	v_mov_b32_e32 v224, s64
	v_mov_b32_e32 v225, s65
	v_cndmask_b32_e64 v222, v222, v224, s[8:9]
	v_cndmask_b32_e64 v223, v223, v225, s[8:9]
	v_mov_b32_e32 v221, 0
	v_lshlrev_b64 v[220:221], 13, v[220:221]
	v_lshl_add_u64 v[220:221], v[220:221], 0, v[222:223]
	v_lshl_add_u64 v[220:221], v[226:227], 2, v[220:221]
	global_load_dwordx4 v[172:175], v[220:221], off
	global_load_dwordx4 v[176:179], v[220:221], off offset:16
	global_load_dwordx4 v[180:183], v[220:221], off offset:512
	global_load_dwordx4 v[184:187], v[220:221], off offset:528
	v_add_u32_e32 v220, 16, v148
	v_add_u32_e32 v221, 0x3ff0, v220
	v_lshrrev_b32_e32 v221, 15, v221
	v_mul_u32_u24_e32 v224, 0x4010, v221
	v_sub_u32_e32 v224, v220, v224
	v_lshlrev_b32_e32 v225, 4, v221
	v_cmp_gt_u32_e64 s[8:9], 16, v224
	v_add_u32_e32 v224, v224, v225
	v_sub_u32_e32 v220, v220, v225
	v_subrev_u32_e32 v220, 16, v220
	v_mov_b32_e32 v222, s68
	v_mov_b32_e32 v223, s69
	v_cndmask_b32_e64 v220, v220, v224, s[8:9]
	v_mov_b32_e32 v224, s64
	v_mov_b32_e32 v225, s65
	v_cndmask_b32_e64 v222, v222, v224, s[8:9]
	v_cndmask_b32_e64 v223, v223, v225, s[8:9]
	v_mov_b32_e32 v221, 0
	v_lshlrev_b64 v[220:221], 13, v[220:221]
	v_lshl_add_u64 v[220:221], v[220:221], 0, v[222:223]
	v_lshl_add_u64 v[220:221], v[226:227], 2, v[220:221]
	global_load_dwordx4 v[188:191], v[220:221], off
	global_load_dwordx4 v[192:195], v[220:221], off offset:16
	global_load_dwordx4 v[196:199], v[220:221], off offset:512
	global_load_dwordx4 v[200:203], v[220:221], off offset:528
	v_add_u32_e32 v220, 32, v148
	v_add_u32_e32 v221, 0x3ff0, v220
	v_lshrrev_b32_e32 v221, 15, v221
	v_mul_u32_u24_e32 v224, 0x4010, v221
	v_sub_u32_e32 v224, v220, v224
	v_lshlrev_b32_e32 v225, 4, v221
	v_cmp_gt_u32_e64 s[8:9], 16, v224
	v_add_u32_e32 v224, v224, v225
	v_sub_u32_e32 v220, v220, v225
	v_subrev_u32_e32 v220, 16, v220
	v_mov_b32_e32 v222, s68
	v_mov_b32_e32 v223, s69
	v_cndmask_b32_e64 v220, v220, v224, s[8:9]
	v_mov_b32_e32 v224, s64
	v_mov_b32_e32 v225, s65
	v_cndmask_b32_e64 v222, v222, v224, s[8:9]
	v_cndmask_b32_e64 v223, v223, v225, s[8:9]
	v_mov_b32_e32 v221, 0
	v_lshlrev_b64 v[220:221], 13, v[220:221]
	v_lshl_add_u64 v[220:221], v[220:221], 0, v[222:223]
	v_lshl_add_u64 v[220:221], v[226:227], 2, v[220:221]
	global_load_dwordx4 v[204:207], v[220:221], off
	global_load_dwordx4 v[208:211], v[220:221], off offset:16
	global_load_dwordx4 v[212:215], v[220:221], off offset:512
	global_load_dwordx4 v[216:219], v[220:221], off offset:528
	v_cmp_lt_i32_e64 s[8:9], s54, v148
	s_nop 1
	v_cndmask_b32_e64 v136, 0, v166, s[8:9]
	v_add_u32_e32 v147, v136, v148
	v_cmp_lt_i32_e64 s[0:1], 15, v147
	v_cndmask_b32_e64 v149, 0, v167, s[8:9]
	s_and_saveexec_b64 s[30:31], s[0:1]
	s_xor_b64 s[30:31], exec, s[30:31]
	v_add3_u32 v136, v147, v149, -16
	v_mov_b64_e32 v[150:151], v[136:137]
	s_or_saveexec_b64 s[30:31], s[30:31]
	v_mov_b64_e32 v[152:153], s[68:69]
	v_cndmask_b32_e64 v136, 0, 16, s[8:9]
	s_xor_b64 exec, exec, s[30:31]
	v_add_u32_e32 v150, v147, v136
	v_ashrrev_i32_e32 v151, 31, v150
	v_mov_b64_e32 v[152:153], s[64:65]
	s_or_b64 exec, exec, s[30:31]
	s_and_saveexec_b64 s[8:9], s[0:1]
	s_xor_b64 s[0:1], exec, s[8:9]
	s_cbranch_execz .LBB0_927
	v_add3_u32 v136, v147, v149, -16
	v_mov_b64_e32 v[156:157], v[136:137]
	s_or_saveexec_b64 s[0:1], s[0:1]
	v_mov_b64_e32 v[158:159], s[92:93]
	s_xor_b64 exec, exec, s[0:1]
	s_cbranch_execnz .LBB0_928
	s_branch .LBB0_929

; __device__ __forceinline__ unsigned cvt_pk_bf16(float lo, float hi) { f32x2_t v = {lo, hi}; bf16x2_t b = __builtin_convertvector(v, bf16x2_t); return __builtin_bit_cast(unsigned, b); }
;     __device__ __forceinline__ void operator()(f32x4 (&acc)[2][2][4][2], const Unit& u, int wr, int wc, int fr, int fq) const {
;     ...
;                     const int col0 = u.pn * BM + wc * 32 + 8 * fq;
; #pragma unroll
;                     for (int bj = 0; bj < 2; ++bj) {
;                         const int col = col0 + bj * HALF;
;                         const f32x4 v0 = *(const f32x4*)(sp + col) + acc[ai][bj][m][0], v1 = *(const f32x4*)(sp + col + 4) + acc[ai][bj][m][1];
;                         if (dp) { *(f32x4*)(dp + col) = v0; *(f32x4*)(dp + col + 4) = v1; }
;                         if (hb) { u32x4 w; w.x = cvt_pk_bf16(v0[0], v0[1]); w.y = cvt_pk_bf16(v0[2], v0[3]); w.z = cvt_pk_bf16(v1[0], v1[1]); w.w = cvt_pk_bf16(v1[2], v1[3]); *(u32x4*)(hb + (size_t)g * DM + col) = w; }
;                         ss += (v0[0] * v0[0] + v0[1] * v0[1]) + (v0[2] * v0[2] + v0[3] * v0[3]) + (v1[0] * v1[0] + v1[1] * v1[1]) + (v1[2] * v1[2] + v1[3] * v1[3]);
.LBB0_929:
	s_or_b64 exec, exec, s[0:1]
	v_lshlrev_b64 v[150:151], 13, v[150:151]
	v_lshl_add_u64 v[150:151], v[152:153], 0, v[150:151]
	v_ashrrev_i32_e32 v147, 31, v146
	v_lshl_add_u64 v[154:155], v[146:147], 2, v[150:151]
	v_lshlrev_b64 v[156:157], 13, v[156:157]
	v_lshl_add_u64 v[156:157], v[158:159], 0, v[156:157]
	v_cmp_ne_u64_e64 s[0:1], 0, v[158:159]
	s_waitcnt vmcnt(8)
	v_pk_add_f32 v[126:127], v[126:127], v[174:175]
	v_pk_add_f32 v[124:125], v[124:125], v[172:173]
	v_pk_add_f32 v[122:123], v[122:123], v[178:179]
	v_pk_add_f32 v[120:121], v[120:121], v[176:177]
	v_lshl_add_u64 v[152:153], v[146:147], 2, v[156:157]
	s_and_saveexec_b64 s[8:9], s[0:1]
	s_cbranch_execz .LBB0_931
	global_store_dwordx4 v[152:153], v[124:127], off
	global_store_dwordx4 v[152:153], v[120:123], off offset:16
.LBB0_931:
	s_or_b64 exec, exec, s[8:9]
	v_ashrrev_i32_e32 v149, 31, v148
	v_lshlrev_b64 v[150:151], 12, v[148:149]
	v_lshl_add_u64 v[150:151], s[84:85], 0, v[150:151]
	v_cvt_pk_bf16_f32 v156, v124, v125
	v_cvt_pk_bf16_f32 v157, v126, v127
	v_cvt_pk_bf16_f32 v158, v120, v121
	v_cvt_pk_bf16_f32 v159, v122, v123
	v_lshl_add_u64 v[150:151], v[146:147], 1, v[150:151]
	global_store_dwordx4 v[150:151], v[156:159], off
	s_nop 0
	v_pk_add_f32 v[118:119], v[118:119], v[182:183]
	v_pk_add_f32 v[116:117], v[116:117], v[180:181]
	v_pk_add_f32 v[114:115], v[114:115], v[186:187]
	v_pk_add_f32 v[112:113], v[112:113], v[184:185]
	v_add_u32_e32 v220, 48, v148
	v_add_u32_e32 v221, 0x3ff0, v220
	v_lshrrev_b32_e32 v221, 15, v221
	v_mul_u32_u24_e32 v224, 0x4010, v221
	v_sub_u32_e32 v224, v220, v224
	v_lshlrev_b32_e32 v225, 4, v221
	v_cmp_gt_u32_e64 s[8:9], 16, v224
	v_add_u32_e32 v224, v224, v225
	v_sub_u32_e32 v220, v220, v225
	v_subrev_u32_e32 v220, 16, v220
	v_mov_b32_e32 v222, s68
	v_mov_b32_e32 v223, s69
	v_cndmask_b32_e64 v220, v220, v224, s[8:9]
	v_mov_b32_e32 v224, s64
	v_mov_b32_e32 v225, s65
	v_cndmask_b32_e64 v222, v222, v224, s[8:9]
	v_cndmask_b32_e64 v223, v223, v225, s[8:9]
	v_mov_b32_e32 v221, 0
	v_lshlrev_b64 v[220:221], 13, v[220:221]
	v_lshl_add_u64 v[220:221], v[220:221], 0, v[222:223]
	v_lshl_add_u64 v[220:221], v[226:227], 2, v[220:221]
	global_load_dwordx4 v[172:175], v[220:221], off
	global_load_dwordx4 v[176:179], v[220:221], off offset:16
	global_load_dwordx4 v[180:183], v[220:221], off offset:512
	global_load_dwordx4 v[184:187], v[220:221], off offset:528
	s_and_saveexec_b64 s[8:9], s[0:1]
	s_cbranch_execz .LBB0_933
	global_store_dwordx4 v[152:153], v[116:119], off offset:512
	global_store_dwordx4 v[152:153], v[112:115], off offset:528

; __device__ __forceinline__ unsigned cvt_pk_bf16(float lo, float hi) { f32x2_t v = {lo, hi}; bf16x2_t b = __builtin_convertvector(v, bf16x2_t); return __builtin_bit_cast(unsigned, b); }
;     __device__ __forceinline__ void operator()(f32x4 (&acc)[2][2][4][2], const Unit& u, int wr, int wc, int fr, int fq) const {
;     ...
;                     const int col0 = u.pn * BM + wc * 32 + 8 * fq;
; #pragma unroll
;                     for (int bj = 0; bj < 2; ++bj) {
;                         const int col = col0 + bj * HALF;
;                         const f32x4 v0 = *(const f32x4*)(sp + col) + acc[ai][bj][m][0], v1 = *(const f32x4*)(sp + col + 4) + acc[ai][bj][m][1];
;                         if (dp) { *(f32x4*)(dp + col) = v0; *(f32x4*)(dp + col + 4) = v1; }
;                         if (hb) { u32x4 w; w.x = cvt_pk_bf16(v0[0], v0[1]); w.y = cvt_pk_bf16(v0[2], v0[3]); w.z = cvt_pk_bf16(v1[0], v1[1]); w.w = cvt_pk_bf16(v1[2], v1[3]); *(u32x4*)(hb + (size_t)g * DM + col) = w; }
;                         ss += (v0[0] * v0[0] + v0[1] * v0[1]) + (v0[2] * v0[2] + v0[3] * v0[3]) + (v1[0] * v1[0] + v1[1] * v1[1]) + (v1[2] * v1[2] + v1[3] * v1[3]);
.LBB0_945:
	s_or_b64 exec, exec, s[0:1]
	v_lshlrev_b64 v[114:115], 13, v[114:115]
	v_lshl_add_u64 v[114:115], v[116:117], 0, v[114:115]
	v_ashrrev_i32_e32 v147, 31, v146
	v_lshl_add_u64 v[118:119], v[146:147], 2, v[114:115]
	v_lshlrev_b64 v[120:121], 13, v[120:121]
	v_lshl_add_u64 v[120:121], v[122:123], 0, v[120:121]
	v_cmp_ne_u64_e64 s[0:1], 0, v[122:123]
	s_waitcnt vmcnt(8)
	v_pk_add_f32 v[110:111], v[110:111], v[190:191]
	v_pk_add_f32 v[108:109], v[108:109], v[188:189]
	v_pk_add_f32 v[106:107], v[106:107], v[194:195]
	v_pk_add_f32 v[104:105], v[104:105], v[192:193]
	v_lshl_add_u64 v[116:117], v[146:147], 2, v[120:121]
	s_and_saveexec_b64 s[8:9], s[0:1]
	s_cbranch_execz .LBB0_947
	global_store_dwordx4 v[116:117], v[108:111], off
	global_store_dwordx4 v[116:117], v[104:107], off offset:16
.LBB0_947:
	s_or_b64 exec, exec, s[8:9]
	v_ashrrev_i32_e32 v113, 31, v112
	v_lshlrev_b64 v[114:115], 12, v[112:113]
	v_lshl_add_u64 v[114:115], s[84:85], 0, v[114:115]
	v_cvt_pk_bf16_f32 v120, v108, v109
	v_cvt_pk_bf16_f32 v121, v110, v111
	v_cvt_pk_bf16_f32 v122, v104, v105
	v_cvt_pk_bf16_f32 v123, v106, v107
	v_lshl_add_u64 v[114:115], v[146:147], 1, v[114:115]
	global_store_dwordx4 v[114:115], v[120:123], off
	s_nop 0
	v_pk_add_f32 v[102:103], v[102:103], v[198:199]
	v_pk_add_f32 v[100:101], v[100:101], v[196:197]
	v_pk_add_f32 v[98:99], v[98:99], v[202:203]
	v_pk_add_f32 v[96:97], v[96:97], v[200:201]
	v_add_u32_e32 v220, 0x80, v148
	v_add_u32_e32 v221, 0x3ff0, v220
	v_lshrrev_b32_e32 v221, 15, v221
	v_mul_u32_u24_e32 v224, 0x4010, v221
	v_sub_u32_e32 v224, v220, v224
	v_lshlrev_b32_e32 v225, 4, v221
	v_cmp_gt_u32_e64 s[8:9], 16, v224
	v_add_u32_e32 v224, v224, v225
	v_sub_u32_e32 v220, v220, v225
	v_subrev_u32_e32 v220, 16, v220
	v_mov_b32_e32 v222, s68
	v_mov_b32_e32 v223, s69
	v_cndmask_b32_e64 v220, v220, v224, s[8:9]
	v_mov_b32_e32 v224, s64
	v_mov_b32_e32 v225, s65
	v_cndmask_b32_e64 v222, v222, v224, s[8:9]
	v_cndmask_b32_e64 v223, v223, v225, s[8:9]
	v_mov_b32_e32 v221, 0
	v_lshlrev_b64 v[220:221], 13, v[220:221]
	v_lshl_add_u64 v[220:221], v[220:221], 0, v[222:223]
	v_lshl_add_u64 v[220:221], v[226:227], 2, v[220:221]
	global_load_dwordx4 v[188:191], v[220:221], off
	global_load_dwordx4 v[192:195], v[220:221], off offset:16
	global_load_dwordx4 v[196:199], v[220:221], off offset:512
	global_load_dwordx4 v[200:203], v[220:221], off offset:528
	s_and_saveexec_b64 s[8:9], s[0:1]
	s_cbranch_execz .LBB0_949
	global_store_dwordx4 v[116:117], v[100:103], off offset:512
	global_store_dwordx4 v[116:117], v[96:99], off offset:528

; __device__ __forceinline__ unsigned cvt_pk_bf16(float lo, float hi) { f32x2_t v = {lo, hi}; bf16x2_t b = __builtin_convertvector(v, bf16x2_t); return __builtin_bit_cast(unsigned, b); }
;     __device__ __forceinline__ void operator()(f32x4 (&acc)[2][2][4][2], const Unit& u, int wr, int wc, int fr, int fq) const {
;     ...
;                     const int col0 = u.pn * BM + wc * 32 + 8 * fq;
; #pragma unroll
;                     for (int bj = 0; bj < 2; ++bj) {
;                         const int col = col0 + bj * HALF;
;                         const f32x4 v0 = *(const f32x4*)(sp + col) + acc[ai][bj][m][0], v1 = *(const f32x4*)(sp + col + 4) + acc[ai][bj][m][1];
;                         if (dp) { *(f32x4*)(dp + col) = v0; *(f32x4*)(dp + col + 4) = v1; }
;                         if (hb) { u32x4 w; w.x = cvt_pk_bf16(v0[0], v0[1]); w.y = cvt_pk_bf16(v0[2], v0[3]); w.z = cvt_pk_bf16(v1[0], v1[1]); w.w = cvt_pk_bf16(v1[2], v1[3]); *(u32x4*)(hb + (size_t)g * DM + col) = w; }
;                         ss += (v0[0] * v0[0] + v0[1] * v0[1]) + (v0[2] * v0[2] + v0[3] * v0[3]) + (v1[0] * v1[0] + v1[1] * v1[1]) + (v1[2] * v1[2] + v1[3] * v1[3]);
.LBB0_961:
	s_or_b64 exec, exec, s[0:1]
	v_lshlrev_b64 v[98:99], 13, v[98:99]
	v_lshl_add_u64 v[98:99], v[100:101], 0, v[98:99]
	v_ashrrev_i32_e32 v147, 31, v146
	v_lshl_add_u64 v[102:103], v[146:147], 2, v[98:99]
	v_lshlrev_b64 v[104:105], 13, v[104:105]
	v_lshl_add_u64 v[104:105], v[106:107], 0, v[104:105]
	v_cmp_ne_u64_e64 s[0:1], 0, v[106:107]
	s_waitcnt vmcnt(8)
	v_pk_add_f32 v[94:95], v[94:95], v[206:207]
	v_pk_add_f32 v[92:93], v[92:93], v[204:205]
	v_pk_add_f32 v[90:91], v[90:91], v[210:211]
	v_pk_add_f32 v[88:89], v[88:89], v[208:209]
	v_lshl_add_u64 v[100:101], v[146:147], 2, v[104:105]
	s_and_saveexec_b64 s[8:9], s[0:1]
	s_cbranch_execz .LBB0_963
	global_store_dwordx4 v[100:101], v[92:95], off
	global_store_dwordx4 v[100:101], v[88:91], off offset:16
.LBB0_963:
	s_or_b64 exec, exec, s[8:9]
	v_ashrrev_i32_e32 v97, 31, v96
	v_lshlrev_b64 v[98:99], 12, v[96:97]
	v_lshl_add_u64 v[98:99], s[84:85], 0, v[98:99]
	v_cvt_pk_bf16_f32 v104, v92, v93
	v_cvt_pk_bf16_f32 v105, v94, v95
	v_cvt_pk_bf16_f32 v106, v88, v89
	v_cvt_pk_bf16_f32 v107, v90, v91
	v_lshl_add_u64 v[98:99], v[146:147], 1, v[98:99]
	global_store_dwordx4 v[98:99], v[104:107], off
	s_nop 0
	v_pk_add_f32 v[86:87], v[86:87], v[214:215]
	v_pk_add_f32 v[84:85], v[84:85], v[212:213]
	v_pk_add_f32 v[82:83], v[82:83], v[218:219]
	v_pk_add_f32 v[80:81], v[80:81], v[216:217]
	v_add_u32_e32 v220, 0x90, v148
	v_add_u32_e32 v221, 0x3ff0, v220
	v_lshrrev_b32_e32 v221, 15, v221
	v_mul_u32_u24_e32 v224, 0x4010, v221
	v_sub_u32_e32 v224, v220, v224
	v_lshlrev_b32_e32 v225, 4, v221
	v_cmp_gt_u32_e64 s[8:9], 16, v224
	v_add_u32_e32 v224, v224, v225
	v_sub_u32_e32 v220, v220, v225
	v_subrev_u32_e32 v220, 16, v220
	v_mov_b32_e32 v222, s68
	v_mov_b32_e32 v223, s69
	v_cndmask_b32_e64 v220, v220, v224, s[8:9]
	v_mov_b32_e32 v224, s64
	v_mov_b32_e32 v225, s65
	v_cndmask_b32_e64 v222, v222, v224, s[8:9]
	v_cndmask_b32_e64 v223, v223, v225, s[8:9]
	v_mov_b32_e32 v221, 0
	v_lshlrev_b64 v[220:221], 13, v[220:221]
	v_lshl_add_u64 v[220:221], v[220:221], 0, v[222:223]
	v_lshl_add_u64 v[220:221], v[226:227], 2, v[220:221]
	global_load_dwordx4 v[204:207], v[220:221], off
	global_load_dwordx4 v[208:211], v[220:221], off offset:16
	global_load_dwordx4 v[212:215], v[220:221], off offset:512
	global_load_dwordx4 v[216:219], v[220:221], off offset:528
	s_and_saveexec_b64 s[8:9], s[0:1]
	s_cbranch_execz .LBB0_965
	global_store_dwordx4 v[100:101], v[84:87], off offset:512
	global_store_dwordx4 v[100:101], v[80:83], off offset:528

; __device__ __forceinline__ unsigned cvt_pk_bf16(float lo, float hi) { f32x2_t v = {lo, hi}; bf16x2_t b = __builtin_convertvector(v, bf16x2_t); return __builtin_bit_cast(unsigned, b); }
;     __device__ __forceinline__ void operator()(f32x4 (&acc)[2][2][4][2], const Unit& u, int wr, int wc, int fr, int fq) const {
;     ...
;                     const int col0 = u.pn * BM + wc * 32 + 8 * fq;
; #pragma unroll
;                     for (int bj = 0; bj < 2; ++bj) {
;                         const int col = col0 + bj * HALF;
;                         const f32x4 v0 = *(const f32x4*)(sp + col) + acc[ai][bj][m][0], v1 = *(const f32x4*)(sp + col + 4) + acc[ai][bj][m][1];
;                         if (dp) { *(f32x4*)(dp + col) = v0; *(f32x4*)(dp + col + 4) = v1; }
;                         if (hb) { u32x4 w; w.x = cvt_pk_bf16(v0[0], v0[1]); w.y = cvt_pk_bf16(v0[2], v0[3]); w.z = cvt_pk_bf16(v1[0], v1[1]); w.w = cvt_pk_bf16(v1[2], v1[3]); *(u32x4*)(hb + (size_t)g * DM + col) = w; }
;                         ss += (v0[0] * v0[0] + v0[1] * v0[1]) + (v0[2] * v0[2] + v0[3] * v0[3]) + (v1[0] * v1[0] + v1[1] * v1[1]) + (v1[2] * v1[2] + v1[3] * v1[3]);
.LBB0_977:
	s_or_b64 exec, exec, s[0:1]
	v_lshlrev_b64 v[82:83], 13, v[82:83]
	v_lshl_add_u64 v[82:83], v[84:85], 0, v[82:83]
	v_ashrrev_i32_e32 v147, 31, v146
	v_lshl_add_u64 v[86:87], v[146:147], 2, v[82:83]
	v_lshlrev_b64 v[88:89], 13, v[88:89]
	v_lshl_add_u64 v[88:89], v[90:91], 0, v[88:89]
	v_cmp_ne_u64_e64 s[0:1], 0, v[90:91]
	s_waitcnt vmcnt(8)
	v_pk_add_f32 v[78:79], v[78:79], v[174:175]
	v_pk_add_f32 v[76:77], v[76:77], v[172:173]
	v_pk_add_f32 v[74:75], v[74:75], v[178:179]
	v_pk_add_f32 v[72:73], v[72:73], v[176:177]
	v_lshl_add_u64 v[84:85], v[146:147], 2, v[88:89]
	s_and_saveexec_b64 s[8:9], s[0:1]
	s_cbranch_execz .LBB0_979
	global_store_dwordx4 v[84:85], v[76:79], off
	global_store_dwordx4 v[84:85], v[72:75], off offset:16
.LBB0_979:
	s_or_b64 exec, exec, s[8:9]
	v_ashrrev_i32_e32 v81, 31, v80
	v_lshlrev_b64 v[82:83], 12, v[80:81]
	v_lshl_add_u64 v[82:83], s[84:85], 0, v[82:83]
	v_cvt_pk_bf16_f32 v88, v76, v77
	v_cvt_pk_bf16_f32 v89, v78, v79
	v_cvt_pk_bf16_f32 v90, v72, v73
	v_cvt_pk_bf16_f32 v91, v74, v75
	v_lshl_add_u64 v[82:83], v[146:147], 1, v[82:83]
	global_store_dwordx4 v[82:83], v[88:91], off
	s_nop 0
	v_pk_add_f32 v[70:71], v[70:71], v[182:183]
	v_pk_add_f32 v[68:69], v[68:69], v[180:181]
	v_pk_add_f32 v[66:67], v[66:67], v[186:187]
	v_pk_add_f32 v[64:65], v[64:65], v[184:185]
	v_add_u32_e32 v220, 0xa0, v148
	v_add_u32_e32 v221, 0x3ff0, v220
	v_lshrrev_b32_e32 v221, 15, v221
	v_mul_u32_u24_e32 v224, 0x4010, v221
	v_sub_u32_e32 v224, v220, v224
	v_lshlrev_b32_e32 v225, 4, v221
	v_cmp_gt_u32_e64 s[8:9], 16, v224
	v_add_u32_e32 v224, v224, v225
	v_sub_u32_e32 v220, v220, v225
	v_subrev_u32_e32 v220, 16, v220
	v_mov_b32_e32 v222, s68
	v_mov_b32_e32 v223, s69
	v_cndmask_b32_e64 v220, v220, v224, s[8:9]
	v_mov_b32_e32 v224, s64
	v_mov_b32_e32 v225, s65
	v_cndmask_b32_e64 v222, v222, v224, s[8:9]
	v_cndmask_b32_e64 v223, v223, v225, s[8:9]
	v_mov_b32_e32 v221, 0
	v_lshlrev_b64 v[220:221], 13, v[220:221]
	v_lshl_add_u64 v[220:221], v[220:221], 0, v[222:223]
	v_lshl_add_u64 v[220:221], v[226:227], 2, v[220:221]
	global_load_dwordx4 v[172:175], v[220:221], off
	global_load_dwordx4 v[176:179], v[220:221], off offset:16
	global_load_dwordx4 v[180:183], v[220:221], off offset:512
	global_load_dwordx4 v[184:187], v[220:221], off offset:528
	s_and_saveexec_b64 s[8:9], s[0:1]
	s_cbranch_execz .LBB0_981
	global_store_dwordx4 v[84:85], v[68:71], off offset:512
	global_store_dwordx4 v[84:85], v[64:67], off offset:528

; __device__ __forceinline__ unsigned cvt_pk_bf16(float lo, float hi) { f32x2_t v = {lo, hi}; bf16x2_t b = __builtin_convertvector(v, bf16x2_t); return __builtin_bit_cast(unsigned, b); }
;     __device__ __forceinline__ void operator()(f32x4 (&acc)[2][2][4][2], const Unit& u, int wr, int wc, int fr, int fq) const {
;     ...
;                     const int col0 = u.pn * BM + wc * 32 + 8 * fq;
; #pragma unroll
;                     for (int bj = 0; bj < 2; ++bj) {
;                         const int col = col0 + bj * HALF;
;                         const f32x4 v0 = *(const f32x4*)(sp + col) + acc[ai][bj][m][0], v1 = *(const f32x4*)(sp + col + 4) + acc[ai][bj][m][1];
;                         if (dp) { *(f32x4*)(dp + col) = v0; *(f32x4*)(dp + col + 4) = v1; }
;                         if (hb) { u32x4 w; w.x = cvt_pk_bf16(v0[0], v0[1]); w.y = cvt_pk_bf16(v0[2], v0[3]); w.z = cvt_pk_bf16(v1[0], v1[1]); w.w = cvt_pk_bf16(v1[2], v1[3]); *(u32x4*)(hb + (size_t)g * DM + col) = w; }
;                         ss += (v0[0] * v0[0] + v0[1] * v0[1]) + (v0[2] * v0[2] + v0[3] * v0[3]) + (v1[0] * v1[0] + v1[1] * v1[1]) + (v1[2] * v1[2] + v1[3] * v1[3]);
.LBB0_993:
	s_or_b64 exec, exec, s[0:1]
	v_lshlrev_b64 v[66:67], 13, v[66:67]
	v_lshl_add_u64 v[66:67], v[68:69], 0, v[66:67]
	v_ashrrev_i32_e32 v147, 31, v146
	v_lshl_add_u64 v[70:71], v[146:147], 2, v[66:67]
	v_lshlrev_b64 v[72:73], 13, v[72:73]
	v_lshl_add_u64 v[72:73], v[74:75], 0, v[72:73]
	v_cmp_ne_u64_e64 s[0:1], 0, v[74:75]
	s_waitcnt vmcnt(8)
	v_pk_add_f32 v[62:63], v[62:63], v[190:191]
	v_pk_add_f32 v[60:61], v[60:61], v[188:189]
	v_pk_add_f32 v[58:59], v[58:59], v[194:195]
	v_pk_add_f32 v[56:57], v[56:57], v[192:193]
	v_lshl_add_u64 v[68:69], v[146:147], 2, v[72:73]
	s_and_saveexec_b64 s[8:9], s[0:1]
	s_cbranch_execz .LBB0_995
	global_store_dwordx4 v[68:69], v[60:63], off
	global_store_dwordx4 v[68:69], v[56:59], off offset:16
.LBB0_995:
	s_or_b64 exec, exec, s[8:9]
	v_ashrrev_i32_e32 v65, 31, v64
	v_lshlrev_b64 v[66:67], 12, v[64:65]
	v_lshl_add_u64 v[66:67], s[84:85], 0, v[66:67]
	v_cvt_pk_bf16_f32 v72, v60, v61
	v_cvt_pk_bf16_f32 v73, v62, v63
	v_cvt_pk_bf16_f32 v74, v56, v57
	v_cvt_pk_bf16_f32 v75, v58, v59
	v_lshl_add_u64 v[66:67], v[146:147], 1, v[66:67]
	global_store_dwordx4 v[66:67], v[72:75], off
	s_nop 0
	v_pk_add_f32 v[54:55], v[54:55], v[198:199]
	v_pk_add_f32 v[52:53], v[52:53], v[196:197]
	v_pk_add_f32 v[50:51], v[50:51], v[202:203]
	v_pk_add_f32 v[48:49], v[48:49], v[200:201]
	v_add_u32_e32 v220, 0xb0, v148
	v_add_u32_e32 v221, 0x3ff0, v220
	v_lshrrev_b32_e32 v221, 15, v221
	v_mul_u32_u24_e32 v224, 0x4010, v221
	v_sub_u32_e32 v224, v220, v224
	v_lshlrev_b32_e32 v225, 4, v221
	v_cmp_gt_u32_e64 s[8:9], 16, v224
	v_add_u32_e32 v224, v224, v225
	v_sub_u32_e32 v220, v220, v225
	v_subrev_u32_e32 v220, 16, v220
	v_mov_b32_e32 v222, s68
	v_mov_b32_e32 v223, s69
	v_cndmask_b32_e64 v220, v220, v224, s[8:9]
	v_mov_b32_e32 v224, s64
	v_mov_b32_e32 v225, s65
	v_cndmask_b32_e64 v222, v222, v224, s[8:9]
	v_cndmask_b32_e64 v223, v223, v225, s[8:9]
	v_mov_b32_e32 v221, 0
	v_lshlrev_b64 v[220:221], 13, v[220:221]
	v_lshl_add_u64 v[220:221], v[220:221], 0, v[222:223]
	v_lshl_add_u64 v[220:221], v[226:227], 2, v[220:221]
	global_load_dwordx4 v[188:191], v[220:221], off
	global_load_dwordx4 v[192:195], v[220:221], off offset:16
	global_load_dwordx4 v[196:199], v[220:221], off offset:512
	global_load_dwordx4 v[200:203], v[220:221], off offset:528
	s_and_saveexec_b64 s[8:9], s[0:1]
	s_cbranch_execz .LBB0_997
	global_store_dwordx4 v[68:69], v[52:55], off offset:512
	global_store_dwordx4 v[68:69], v[48:51], off offset:528

; __device__ __forceinline__ unsigned cvt_pk_bf16(float lo, float hi) { f32x2_t v = {lo, hi}; bf16x2_t b = __builtin_convertvector(v, bf16x2_t); return __builtin_bit_cast(unsigned, b); }
;     __device__ __forceinline__ void operator()(f32x4 (&acc)[2][2][4][2], const Unit& u, int wr, int wc, int fr, int fq) const {
;     ...
;                     const int col0 = u.pn * BM + wc * 32 + 8 * fq;
; #pragma unroll
;                     for (int bj = 0; bj < 2; ++bj) {
;                         const int col = col0 + bj * HALF;
;                         const f32x4 v0 = *(const f32x4*)(sp + col) + acc[ai][bj][m][0], v1 = *(const f32x4*)(sp + col + 4) + acc[ai][bj][m][1];
;                         if (dp) { *(f32x4*)(dp + col) = v0; *(f32x4*)(dp + col + 4) = v1; }
;                         if (hb) { u32x4 w; w.x = cvt_pk_bf16(v0[0], v0[1]); w.y = cvt_pk_bf16(v0[2], v0[3]); w.z = cvt_pk_bf16(v1[0], v1[1]); w.w = cvt_pk_bf16(v1[2], v1[3]); *(u32x4*)(hb + (size_t)g * DM + col) = w; }
;                         ss += (v0[0] * v0[0] + v0[1] * v0[1]) + (v0[2] * v0[2] + v0[3] * v0[3]) + (v1[0] * v1[0] + v1[1] * v1[1]) + (v1[2] * v1[2] + v1[3] * v1[3]);
.LBB0_1009:
	s_or_b64 exec, exec, s[0:1]
	v_lshlrev_b64 v[50:51], 13, v[50:51]
	v_lshl_add_u64 v[50:51], v[52:53], 0, v[50:51]
	v_ashrrev_i32_e32 v147, 31, v146
	v_lshl_add_u64 v[54:55], v[146:147], 2, v[50:51]
	v_lshlrev_b64 v[56:57], 13, v[56:57]
	v_lshl_add_u64 v[56:57], v[58:59], 0, v[56:57]
	v_cmp_ne_u64_e64 s[0:1], 0, v[58:59]
	s_waitcnt vmcnt(8)
	v_pk_add_f32 v[46:47], v[46:47], v[206:207]
	v_pk_add_f32 v[44:45], v[44:45], v[204:205]
	v_pk_add_f32 v[42:43], v[42:43], v[210:211]
	v_pk_add_f32 v[40:41], v[40:41], v[208:209]
	v_lshl_add_u64 v[52:53], v[146:147], 2, v[56:57]
	s_and_saveexec_b64 s[8:9], s[0:1]
	s_cbranch_execz .LBB0_1011
	global_store_dwordx4 v[52:53], v[44:47], off
	global_store_dwordx4 v[52:53], v[40:43], off offset:16
.LBB0_1011:
	s_or_b64 exec, exec, s[8:9]
	v_ashrrev_i32_e32 v49, 31, v48
	v_lshlrev_b64 v[50:51], 12, v[48:49]
	v_lshl_add_u64 v[50:51], s[84:85], 0, v[50:51]
	v_cvt_pk_bf16_f32 v56, v44, v45
	v_cvt_pk_bf16_f32 v57, v46, v47
	v_cvt_pk_bf16_f32 v58, v40, v41
	v_cvt_pk_bf16_f32 v59, v42, v43
	v_lshl_add_u64 v[50:51], v[146:147], 1, v[50:51]
	global_store_dwordx4 v[50:51], v[56:59], off
	s_nop 0
	v_pk_add_f32 v[38:39], v[38:39], v[214:215]
	v_pk_add_f32 v[36:37], v[36:37], v[212:213]
	v_pk_add_f32 v[34:35], v[34:35], v[218:219]
	v_pk_add_f32 v[32:33], v[32:33], v[216:217]
	s_and_saveexec_b64 s[8:9], s[0:1]
	s_cbranch_execz .LBB0_1013
	global_store_dwordx4 v[52:53], v[36:39], off offset:512
	global_store_dwordx4 v[52:53], v[32:35], off offset:528

; __device__ __forceinline__ unsigned cvt_pk_bf16(float lo, float hi) { f32x2_t v = {lo, hi}; bf16x2_t b = __builtin_convertvector(v, bf16x2_t); return __builtin_bit_cast(unsigned, b); }
;     __device__ __forceinline__ void operator()(f32x4 (&acc)[2][2][4][2], const Unit& u, int wr, int wc, int fr, int fq) const {
;     ...
;                     const int col0 = u.pn * BM + wc * 32 + 8 * fq;
; #pragma unroll
;                     for (int bj = 0; bj < 2; ++bj) {
;                         const int col = col0 + bj * HALF;
;                         const f32x4 v0 = *(const f32x4*)(sp + col) + acc[ai][bj][m][0], v1 = *(const f32x4*)(sp + col + 4) + acc[ai][bj][m][1];
;                         if (dp) { *(f32x4*)(dp + col) = v0; *(f32x4*)(dp + col + 4) = v1; }
;                         if (hb) { u32x4 w; w.x = cvt_pk_bf16(v0[0], v0[1]); w.y = cvt_pk_bf16(v0[2], v0[3]); w.z = cvt_pk_bf16(v1[0], v1[1]); w.w = cvt_pk_bf16(v1[2], v1[3]); *(u32x4*)(hb + (size_t)g * DM + col) = w; }
;                         ss += (v0[0] * v0[0] + v0[1] * v0[1]) + (v0[2] * v0[2] + v0[3] * v0[3]) + (v1[0] * v1[0] + v1[1] * v1[1]) + (v1[2] * v1[2] + v1[3] * v1[3]);
.LBB0_1025:
	s_or_b64 exec, exec, s[0:1]
	v_lshlrev_b64 v[34:35], 13, v[34:35]
	v_lshl_add_u64 v[34:35], v[36:37], 0, v[34:35]
	v_ashrrev_i32_e32 v147, 31, v146
	v_lshl_add_u64 v[38:39], v[146:147], 2, v[34:35]
	v_lshlrev_b64 v[40:41], 13, v[40:41]
	v_lshl_add_u64 v[40:41], v[42:43], 0, v[40:41]
	v_cmp_ne_u64_e64 s[0:1], 0, v[42:43]
	s_waitcnt vmcnt(4)
	v_pk_add_f32 v[30:31], v[30:31], v[174:175]
	v_pk_add_f32 v[28:29], v[28:29], v[172:173]
	v_pk_add_f32 v[26:27], v[26:27], v[178:179]
	v_pk_add_f32 v[24:25], v[24:25], v[176:177]
	v_lshl_add_u64 v[36:37], v[146:147], 2, v[40:41]
	s_and_saveexec_b64 s[8:9], s[0:1]
	s_cbranch_execz .LBB0_1027
	global_store_dwordx4 v[36:37], v[28:31], off
	global_store_dwordx4 v[36:37], v[24:27], off offset:16
.LBB0_1027:
	s_or_b64 exec, exec, s[8:9]
	v_ashrrev_i32_e32 v33, 31, v32
	v_lshlrev_b64 v[34:35], 12, v[32:33]
	v_lshl_add_u64 v[34:35], s[84:85], 0, v[34:35]
	v_cvt_pk_bf16_f32 v40, v28, v29
	v_cvt_pk_bf16_f32 v41, v30, v31
	v_cvt_pk_bf16_f32 v42, v24, v25
	v_cvt_pk_bf16_f32 v43, v26, v27
	v_lshl_add_u64 v[34:35], v[146:147], 1, v[34:35]
	global_store_dwordx4 v[34:35], v[40:43], off
	s_nop 0
	v_pk_add_f32 v[22:23], v[22:23], v[182:183]
	v_pk_add_f32 v[20:21], v[20:21], v[180:181]
	v_pk_add_f32 v[18:19], v[18:19], v[186:187]
	v_pk_add_f32 v[16:17], v[16:17], v[184:185]
	s_and_saveexec_b64 s[8:9], s[0:1]
	s_cbranch_execz .LBB0_1029
	global_store_dwordx4 v[36:37], v[20:23], off offset:512
	global_store_dwordx4 v[36:37], v[16:19], off offset:528

; __device__ __forceinline__ unsigned cvt_pk_bf16(float lo, float hi) { f32x2_t v = {lo, hi}; bf16x2_t b = __builtin_convertvector(v, bf16x2_t); return __builtin_bit_cast(unsigned, b); }
;     __device__ __forceinline__ void operator()(f32x4 (&acc)[2][2][4][2], const Unit& u, int wr, int wc, int fr, int fq) const {
;     ...
;                     const int col0 = u.pn * BM + wc * 32 + 8 * fq;
; #pragma unroll
;                     for (int bj = 0; bj < 2; ++bj) {
;                         const int col = col0 + bj * HALF;
;                         const f32x4 v0 = *(const f32x4*)(sp + col) + acc[ai][bj][m][0], v1 = *(const f32x4*)(sp + col + 4) + acc[ai][bj][m][1];
;                         if (dp) { *(f32x4*)(dp + col) = v0; *(f32x4*)(dp + col + 4) = v1; }
;                         if (hb) { u32x4 w; w.x = cvt_pk_bf16(v0[0], v0[1]); w.y = cvt_pk_bf16(v0[2], v0[3]); w.z = cvt_pk_bf16(v1[0], v1[1]); w.w = cvt_pk_bf16(v1[2], v1[3]); *(u32x4*)(hb + (size_t)g * DM + col) = w; }
;                         ss += (v0[0] * v0[0] + v0[1] * v0[1]) + (v0[2] * v0[2] + v0[3] * v0[3]) + (v1[0] * v1[0] + v1[1] * v1[1]) + (v1[2] * v1[2] + v1[3] * v1[3]);
.LBB0_1041:
	s_or_b64 exec, exec, s[0:1]
	v_lshlrev_b64 v[18:19], 13, v[18:19]
	v_lshl_add_u64 v[18:19], v[20:21], 0, v[18:19]
	v_ashrrev_i32_e32 v147, 31, v146
	v_lshl_add_u64 v[22:23], v[146:147], 2, v[18:19]
	v_lshlrev_b64 v[24:25], 13, v[24:25]
	v_lshl_add_u64 v[24:25], v[26:27], 0, v[24:25]
	v_cmp_ne_u64_e64 s[0:1], 0, v[26:27]
	s_waitcnt vmcnt(0)
	v_pk_add_f32 v[14:15], v[14:15], v[190:191]
	v_pk_add_f32 v[12:13], v[12:13], v[188:189]
	v_pk_add_f32 v[10:11], v[10:11], v[194:195]
	v_pk_add_f32 v[8:9], v[8:9], v[192:193]
	v_lshl_add_u64 v[20:21], v[146:147], 2, v[24:25]
	s_and_saveexec_b64 s[8:9], s[0:1]
	s_cbranch_execz .LBB0_1043
	global_store_dwordx4 v[20:21], v[12:15], off
	global_store_dwordx4 v[20:21], v[8:11], off offset:16
.LBB0_1043:
	s_or_b64 exec, exec, s[8:9]
	v_ashrrev_i32_e32 v17, 31, v16
	v_lshlrev_b64 v[18:19], 12, v[16:17]
	v_lshl_add_u64 v[18:19], s[84:85], 0, v[18:19]
	v_cvt_pk_bf16_f32 v24, v12, v13
	v_cvt_pk_bf16_f32 v25, v14, v15
	v_cvt_pk_bf16_f32 v26, v8, v9
	v_cvt_pk_bf16_f32 v27, v10, v11
	v_lshl_add_u64 v[18:19], v[146:147], 1, v[18:19]
	global_store_dwordx4 v[18:19], v[24:27], off
	s_nop 0
	v_pk_add_f32 v[6:7], v[6:7], v[198:199]
	v_pk_add_f32 v[4:5], v[4:5], v[196:197]
	v_pk_add_f32 v[2:3], v[2:3], v[202:203]
	v_pk_add_f32 v[0:1], v[0:1], v[200:201]
	s_and_saveexec_b64 s[8:9], s[0:1]
	s_cbranch_execz .LBB0_1045
	global_store_dwordx4 v[20:21], v[4:7], off offset:512
	global_store_dwordx4 v[20:21], v[0:3], off offset:528

;     __device__ __forceinline__ void operator()(f32x4 (&acc)[2][2][4][2], const Unit& u, int wr, int wc, int fr_in, int fq_in) const {
;     ...
;         const int b = u.pm / 65, jt = u.pm % 65, tb = jt * 254 - 1;
; #pragma unroll
;         for (int ai = 0; ai < 2; ++ai)
; #pragma unroll
;             for (int m = 0; m < 4; ++m) {
;                 const int t = tb + ai * HALF + wr * 64 + m * 16 + fr; const bool ok = (t >= 0) && (t < T);
;                 const float rs = ok ? rsqrtf(ssq[b * T + (ok ? t : 0)] * (1.0f / DM) + EPS) : 0.f;
; #pragma unroll
;                 for (int bj = 0; bj < 2; ++bj)
; #pragma unroll
;                     for (int n = 0; n < 2; ++n)
; #pragma unroll
;                         for (int e = 0; e < 4; ++e) acc[ai][bj][m][n][e] = acc[ai][bj][m][n][e] * rs;
;             }
.LBB0_1120:
	s_mul_hi_i32 s0, s33, 0x7e07e07f
	s_lshr_b32 s1, s0, 31
	s_ashr_i32 s0, s0, 5
	s_add_i32 s29, s0, s1
	s_mul_i32 s0, s29, 0x41
	s_sub_i32 s81, s33, s0
	s_mulk_i32 s81, 0xfe
	s_add_i32 s33, s81, -1
	v_mbcnt_lo_u32_b32 v145, -1, 0
	v_mbcnt_hi_u32_b32 v145, -1, v145
	s_add_i32 s0, s33, s51
	v_and_b32_e32 v181, 15, v145
	v_add_u32_e32 v146, s0, v181
	s_mulk_i32 s29, 0x4010
	v_add_u32_e32 v232, s29, v146
	v_ashrrev_i32_e32 v233, 31, v232
	v_lshl_add_u64 v[232:233], v[232:233], 2, s[12:13]
	global_load_dword v224, v[232:233], off
	global_load_dword v225, v[232:233], off offset:64
	global_load_dword v226, v[232:233], off offset:128
	global_load_dword v227, v[232:233], off offset:192
	global_load_dword v228, v[232:233], off offset:512
	global_load_dword v229, v[232:233], off offset:576
	global_load_dword v230, v[232:233], off offset:640
	global_load_dword v231, v[232:233], off offset:704
	s_waitcnt vmcnt(0)
	v_cmp_gt_u32_e32 vcc, s49, v146
	v_mov_b32_e32 v162, 0
	v_mov_b32_e32 v202, 0
	s_and_saveexec_b64 s[0:1], vcc
	s_cbranch_execz .LBB0_1122
	v_add_u32_e32 v148, s29, v146
	v_ashrrev_i32_e32 v149, 31, v148
	v_lshl_add_u64 v[148:149], v[148:149], 2, s[12:13]
	v_mov_b32_e32 v144, v224
	v_fmamk_f32 v144, v144, 0x3a000000, v251
	v_mul_f32_e32 v147, 0x4b800000, v144
	v_cmp_gt_f32_e32 vcc, s77, v144
	s_nop 1
	v_cndmask_b32_e32 v144, v144, v147, vcc
	v_rsq_f32_e32 v144, v144
	s_nop 0
	v_mul_f32_e32 v147, 0x45800000, v144
	v_cndmask_b32_e32 v202, v144, v147, vcc
.LBB0_1122:
	s_or_b64 exec, exec, s[0:1]
	v_add_u32_e32 v144, 16, v146
	v_cmp_gt_u32_e32 vcc, s49, v144
	s_and_saveexec_b64 s[0:1], vcc
	s_cbranch_execz .LBB0_1124
	v_add_u32_e32 v148, s29, v144
	v_ashrrev_i32_e32 v149, 31, v148
	v_lshl_add_u64 v[148:149], v[148:149], 2, s[12:13]
	v_mov_b32_e32 v144, v225
	v_fmamk_f32 v144, v144, 0x3a000000, v251
	v_mul_f32_e32 v147, 0x4b800000, v144
	v_cmp_gt_f32_e32 vcc, s77, v144
	s_nop 1
	v_cndmask_b32_e32 v144, v144, v147, vcc
	v_rsq_f32_e32 v144, v144
	s_nop 0
	v_mul_f32_e32 v147, 0x45800000, v144
	v_cndmask_b32_e32 v162, v144, v147, vcc
.LBB0_1124:
	s_or_b64 exec, exec, s[0:1]
	v_add_u32_e32 v144, 32, v146
	v_cmp_gt_u32_e32 vcc, s49, v144
	v_mov_b32_e32 v186, 0
	v_mov_b32_e32 v198, 0
	s_and_saveexec_b64 s[0:1], vcc
	s_cbranch_execz .LBB0_1126
	v_add_u32_e32 v148, s29, v144
	v_ashrrev_i32_e32 v149, 31, v148
	v_lshl_add_u64 v[148:149], v[148:149], 2, s[12:13]
	v_mov_b32_e32 v144, v226
	v_fmamk_f32 v144, v144, 0x3a000000, v251
	v_mul_f32_e32 v147, 0x4b800000, v144
	v_cmp_gt_f32_e32 vcc, s77, v144
	s_nop 1
	v_cndmask_b32_e32 v144, v144, v147, vcc
	v_rsq_f32_e32 v144, v144
	s_nop 0
	v_mul_f32_e32 v147, 0x45800000, v144
	v_cndmask_b32_e32 v198, v144, v147, vcc
.LBB0_1126:
	s_or_b64 exec, exec, s[0:1]
	v_add_u32_e32 v144, 48, v146
	v_cmp_gt_u32_e32 vcc, s49, v144
	s_and_saveexec_b64 s[0:1], vcc
	s_cbranch_execz .LBB0_1128
	v_add_u32_e32 v148, s29, v144
	v_ashrrev_i32_e32 v149, 31, v148
	v_lshl_add_u64 v[148:149], v[148:149], 2, s[12:13]
	v_mov_b32_e32 v144, v227
	v_fmamk_f32 v144, v144, 0x3a000000, v251
	v_mul_f32_e32 v147, 0x4b800000, v144
	v_cmp_gt_f32_e32 vcc, s77, v144
	s_nop 1
	v_cndmask_b32_e32 v144, v144, v147, vcc
	v_rsq_f32_e32 v144, v144
	s_nop 0
	v_mul_f32_e32 v147, 0x45800000, v144
	v_cndmask_b32_e32 v186, v144, v147, vcc
.LBB0_1128:
	s_or_b64 exec, exec, s[0:1]
	v_add_u32_e32 v144, 0x80, v146
	v_cmp_gt_u32_e32 vcc, s49, v144
	v_mov_b32_e32 v180, 0
	v_mov_b32_e32 v164, 0
	s_and_saveexec_b64 s[0:1], vcc
	s_cbranch_execz .LBB0_1130
	v_add_u32_e32 v148, s29, v144
	v_ashrrev_i32_e32 v149, 31, v148
	v_lshl_add_u64 v[148:149], v[148:149], 2, s[12:13]
	v_mov_b32_e32 v144, v228
	v_fmamk_f32 v144, v144, 0x3a000000, v251
	v_mul_f32_e32 v147, 0x4b800000, v144
	v_cmp_gt_f32_e32 vcc, s77, v144
	s_nop 1
	v_cndmask_b32_e32 v144, v144, v147, vcc
	v_rsq_f32_e32 v144, v144
	s_nop 0
	v_mul_f32_e32 v147, 0x45800000, v144
	v_cndmask_b32_e32 v164, v144, v147, vcc
.LBB0_1130:
	s_or_b64 exec, exec, s[0:1]
	v_add_u32_e32 v144, 0x90, v146
	v_cmp_gt_u32_e32 vcc, s49, v144
	s_and_saveexec_b64 s[0:1], vcc
	s_cbranch_execz .LBB0_1132
	v_add_u32_e32 v148, s29, v144
	v_ashrrev_i32_e32 v149, 31, v148
	v_lshl_add_u64 v[148:149], v[148:149], 2, s[12:13]
	v_mov_b32_e32 v144, v229
	v_fmamk_f32 v144, v144, 0x3a000000, v251
	v_mul_f32_e32 v147, 0x4b800000, v144
	v_cmp_gt_f32_e32 vcc, s77, v144
	s_nop 1
	v_cndmask_b32_e32 v144, v144, v147, vcc
	v_rsq_f32_e32 v144, v144
	s_nop 0
	v_mul_f32_e32 v147, 0x45800000, v144
	v_cndmask_b32_e32 v180, v144, v147, vcc
.LBB0_1132:
	s_or_b64 exec, exec, s[0:1]
	v_add_u32_e32 v147, 0xa0, v146
	v_cmp_gt_u32_e32 vcc, s49, v147
	v_mov_b32_e32 v144, 0
	v_mov_b32_e32 v160, 0
	s_and_saveexec_b64 s[0:1], vcc
	s_cbranch_execz .LBB0_1134
	v_add_u32_e32 v148, s29, v147
	v_ashrrev_i32_e32 v149, 31, v148
	v_lshl_add_u64 v[148:149], v[148:149], 2, s[12:13]
	v_mov_b32_e32 v147, v230
	v_fmamk_f32 v147, v147, 0x3a000000, v251
	v_mul_f32_e32 v148, 0x4b800000, v147
	v_cmp_gt_f32_e32 vcc, s77, v147
	s_nop 1
	v_cndmask_b32_e32 v147, v147, v148, vcc
	v_rsq_f32_e32 v147, v147
	s_nop 0
	v_mul_f32_e32 v148, 0x45800000, v147
	v_cndmask_b32_e32 v160, v147, v148, vcc
.LBB0_1134:
	s_or_b64 exec, exec, s[0:1]
	v_add_u32_e32 v146, 0xb0, v146
	v_cmp_gt_u32_e32 vcc, s49, v146
	s_and_saveexec_b64 s[0:1], vcc
	s_cbranch_execz .LBB0_1136
	v_add_u32_e32 v146, s29, v146
	v_ashrrev_i32_e32 v147, 31, v146
	v_lshl_add_u64 v[146:147], v[146:147], 2, s[12:13]
	v_mov_b32_e32 v144, v231
	v_fmamk_f32 v144, v144, 0x3a000000, v251
	v_mul_f32_e32 v146, 0x4b800000, v144
	v_cmp_gt_f32_e32 vcc, s77, v144
	s_nop 1
	v_cndmask_b32_e32 v144, v144, v146, vcc
	v_rsq_f32_e32 v144, v144
	s_nop 0
	v_mul_f32_e32 v146, 0x45800000, v144
	v_cndmask_b32_e32 v144, v144, v146, vcc

; __device__ __forceinline__ unsigned cvt_pk_bf16(float lo, float hi) { f32x2_t v = {lo, hi}; bf16x2_t b = __builtin_convertvector(v, bf16x2_t); return __builtin_bit_cast(unsigned, b); }
;     __device__ __forceinline__ void operator()(f32x4 (&acc)[2][2][4][2], const Unit& u, int wr, int wc, int fr, int fq) const {
;     ...
;         for (int ai = 0; ai < 2; ++ai)
; #pragma unroll
;             for (int m = 0; m < 4; ++m) {
;                 const int g = u.pm * BM + ai * HALF + wr * 64 + m * 16 + fr; float ss = 0.f;
;                 if (g < M) {
;                     const int b = g >= T ? 1 : 0, t = g - b * T;
;                     const float* sp = t < 16 ? srcm + (size_t)(b * 16 + t) * DM : srcx + ((size_t)b * SEQ + (t - 16)) * DM;
;                     float* dp = t < 16 ? (dstm ? dstm + (size_t)(b * 16 + t) * DM : (float*)nullptr) : dstx + ((size_t)b * SEQ + (t - 16)) * DM;
;                     const int col0 = u.pn * BM + wc * 32 + 8 * fq;
; #pragma unroll
;                     for (int bj = 0; bj < 2; ++bj) {
;                         const int col = col0 + bj * HALF;
;                         const f32x4 v0 = *(const f32x4*)(sp + col) + acc[ai][bj][m][0], v1 = *(const f32x4*)(sp + col + 4) + acc[ai][bj][m][1];
;                         if (dp) { *(f32x4*)(dp + col) = v0; *(f32x4*)(dp + col + 4) = v1; }
;                         if (hb) { u32x4 w; w.x = cvt_pk_bf16(v0[0], v0[1]); w.y = cvt_pk_bf16(v0[2], v0[3]); w.z = cvt_pk_bf16(v1[0], v1[1]); w.w = cvt_pk_bf16(v1[2], v1[3]); *(u32x4*)(hb + (size_t)g * DM + col) = w; }
;                         ss += (v0[0] * v0[0] + v0[1] * v0[1]) + (v0[2] * v0[2] + v0[3] * v0[3]) + (v1[0] * v1[0] + v1[1] * v1[1]) + (v1[2] * v1[2] + v1[3] * v1[3]);
.LBB0_1316:
	v_lshl_add_u32 v148, s33, 8, v160
	v_lshl_or_b32 v146, s51, 8, v162
	v_cmp_gt_i32_e32 vcc, s47, v148
	v_mov_b32_e32 v136, 0
	s_and_saveexec_b64 s[26:27], vcc
	s_cbranch_execz .LBB0_1330
	v_mov_b32_e32 v226, v146
	v_mov_b32_e32 v227, 0
	v_mov_b32_e32 v220, v148
	v_add_u32_e32 v221, 0x3ff0, v220
	v_lshrrev_b32_e32 v221, 15, v221
	v_mul_u32_u24_e32 v224, 0x4010, v221
	v_sub_u32_e32 v224, v220, v224
	v_lshlrev_b32_e32 v225, 4, v221
	v_cmp_gt_u32_e64 s[12:13], 16, v224
	v_add_u32_e32 v224, v224, v225
	v_sub_u32_e32 v220, v220, v225
	v_subrev_u32_e32 v220, 16, v220
	v_mov_b32_e32 v222, s92
	v_mov_b32_e32 v223, s93
	v_cndmask_b32_e64 v220, v220, v224, s[12:13]
	v_mov_b32_e32 v224, s64
	v_mov_b32_e32 v225, s65
	v_cndmask_b32_e64 v222, v222, v224, s[12:13]
	v_cndmask_b32_e64 v223, v223, v225, s[12:13]
	v_mov_b32_e32 v221, 0
	v_lshlrev_b64 v[220:221], 13, v[220:221]
	v_lshl_add_u64 v[220:221], v[220:221], 0, v[222:223]
	v_lshl_add_u64 v[220:221], v[226:227], 2, v[220:221]
	global_load_dwordx4 v[172:175], v[220:221], off
	global_load_dwordx4 v[176:179], v[220:221], off offset:16
	global_load_dwordx4 v[180:183], v[220:221], off offset:512
	global_load_dwordx4 v[184:187], v[220:221], off offset:528
	v_add_u32_e32 v220, 16, v148
	v_add_u32_e32 v221, 0x3ff0, v220
	v_lshrrev_b32_e32 v221, 15, v221
	v_mul_u32_u24_e32 v224, 0x4010, v221
	v_sub_u32_e32 v224, v220, v224
	v_lshlrev_b32_e32 v225, 4, v221
	v_cmp_gt_u32_e64 s[12:13], 16, v224
	v_add_u32_e32 v224, v224, v225
	v_sub_u32_e32 v220, v220, v225
	v_subrev_u32_e32 v220, 16, v220
	v_mov_b32_e32 v222, s92
	v_mov_b32_e32 v223, s93
	v_cndmask_b32_e64 v220, v220, v224, s[12:13]
	v_mov_b32_e32 v224, s64
	v_mov_b32_e32 v225, s65
	v_cndmask_b32_e64 v222, v222, v224, s[12:13]
	v_cndmask_b32_e64 v223, v223, v225, s[12:13]
	v_mov_b32_e32 v221, 0
	v_lshlrev_b64 v[220:221], 13, v[220:221]
	v_lshl_add_u64 v[220:221], v[220:221], 0, v[222:223]
	v_lshl_add_u64 v[220:221], v[226:227], 2, v[220:221]
	global_load_dwordx4 v[188:191], v[220:221], off
	global_load_dwordx4 v[192:195], v[220:221], off offset:16
	global_load_dwordx4 v[196:199], v[220:221], off offset:512
	global_load_dwordx4 v[200:203], v[220:221], off offset:528
	v_add_u32_e32 v220, 32, v148
	v_add_u32_e32 v221, 0x3ff0, v220
	v_lshrrev_b32_e32 v221, 15, v221
	v_mul_u32_u24_e32 v224, 0x4010, v221
	v_sub_u32_e32 v224, v220, v224
	v_lshlrev_b32_e32 v225, 4, v221
	v_cmp_gt_u32_e64 s[12:13], 16, v224
	v_add_u32_e32 v224, v224, v225
	v_sub_u32_e32 v220, v220, v225
	v_subrev_u32_e32 v220, 16, v220
	v_mov_b32_e32 v222, s92
	v_mov_b32_e32 v223, s93
	v_cndmask_b32_e64 v220, v220, v224, s[12:13]
	v_mov_b32_e32 v224, s64
	v_mov_b32_e32 v225, s65
	v_cndmask_b32_e64 v222, v222, v224, s[12:13]
	v_cndmask_b32_e64 v223, v223, v225, s[12:13]
	v_mov_b32_e32 v221, 0
	v_lshlrev_b64 v[220:221], 13, v[220:221]
	v_lshl_add_u64 v[220:221], v[220:221], 0, v[222:223]
	v_lshl_add_u64 v[220:221], v[226:227], 2, v[220:221]
	global_load_dwordx4 v[204:207], v[220:221], off
	global_load_dwordx4 v[208:211], v[220:221], off offset:16
	global_load_dwordx4 v[212:215], v[220:221], off offset:512
	global_load_dwordx4 v[216:219], v[220:221], off offset:528
	v_cmp_lt_i32_e64 s[12:13], s48, v148
	s_nop 1
	v_cndmask_b32_e64 v136, 0, v166, s[12:13]
	v_add_u32_e32 v147, v136, v148
	v_cmp_lt_i32_e64 s[0:1], 15, v147
	v_cndmask_b32_e64 v149, 0, v167, s[12:13]
	s_and_saveexec_b64 s[28:29], s[0:1]
	s_xor_b64 s[28:29], exec, s[28:29]
	v_add3_u32 v136, v147, v149, -16
	v_mov_b64_e32 v[150:151], v[136:137]
	s_or_saveexec_b64 s[28:29], s[28:29]
	v_mov_b64_e32 v[152:153], s[92:93]
	v_cndmask_b32_e64 v136, 0, 16, s[12:13]
	s_xor_b64 exec, exec, s[28:29]
	v_add_u32_e32 v150, v147, v136
	v_ashrrev_i32_e32 v151, 31, v150
	v_mov_b64_e32 v[152:153], s[64:65]
	s_or_b64 exec, exec, s[28:29]
	s_and_saveexec_b64 s[12:13], s[0:1]
	s_xor_b64 s[0:1], exec, s[12:13]
	s_cbranch_execz .LBB0_1323
	v_add3_u32 v136, v147, v149, -16
	v_mov_b64_e32 v[156:157], v[136:137]
	s_or_saveexec_b64 s[0:1], s[0:1]
	v_mov_b64_e32 v[158:159], s[92:93]
	s_xor_b64 exec, exec, s[0:1]
	s_cbranch_execnz .LBB0_1324
	s_branch .LBB0_1325

; __device__ __forceinline__ unsigned cvt_pk_bf16(float lo, float hi) { f32x2_t v = {lo, hi}; bf16x2_t b = __builtin_convertvector(v, bf16x2_t); return __builtin_bit_cast(unsigned, b); }
;     __device__ __forceinline__ void operator()(f32x4 (&acc)[2][2][4][2], const Unit& u, int wr, int wc, int fr, int fq) const {
;     ...
;                     const int col0 = u.pn * BM + wc * 32 + 8 * fq;
; #pragma unroll
;                     for (int bj = 0; bj < 2; ++bj) {
;                         const int col = col0 + bj * HALF;
;                         const f32x4 v0 = *(const f32x4*)(sp + col) + acc[ai][bj][m][0], v1 = *(const f32x4*)(sp + col + 4) + acc[ai][bj][m][1];
;                         if (dp) { *(f32x4*)(dp + col) = v0; *(f32x4*)(dp + col + 4) = v1; }
;                         if (hb) { u32x4 w; w.x = cvt_pk_bf16(v0[0], v0[1]); w.y = cvt_pk_bf16(v0[2], v0[3]); w.z = cvt_pk_bf16(v1[0], v1[1]); w.w = cvt_pk_bf16(v1[2], v1[3]); *(u32x4*)(hb + (size_t)g * DM + col) = w; }
;                         ss += (v0[0] * v0[0] + v0[1] * v0[1]) + (v0[2] * v0[2] + v0[3] * v0[3]) + (v1[0] * v1[0] + v1[1] * v1[1]) + (v1[2] * v1[2] + v1[3] * v1[3]);
.LBB0_1325:
	s_or_b64 exec, exec, s[0:1]
	v_lshlrev_b64 v[150:151], 13, v[150:151]
	v_lshl_add_u64 v[150:151], v[152:153], 0, v[150:151]
	v_ashrrev_i32_e32 v147, 31, v146
	v_lshl_add_u64 v[154:155], v[146:147], 2, v[150:151]
	v_lshlrev_b64 v[156:157], 13, v[156:157]
	v_lshl_add_u64 v[156:157], v[158:159], 0, v[156:157]
	v_cmp_ne_u64_e64 s[0:1], 0, v[158:159]
	s_waitcnt vmcnt(8)
	v_pk_add_f32 v[126:127], v[126:127], v[174:175]
	v_pk_add_f32 v[124:125], v[124:125], v[172:173]
	v_pk_add_f32 v[122:123], v[122:123], v[178:179]
	v_pk_add_f32 v[120:121], v[120:121], v[176:177]
	v_lshl_add_u64 v[152:153], v[146:147], 2, v[156:157]
	s_and_saveexec_b64 s[12:13], s[0:1]
	s_cbranch_execz .LBB0_1327
	global_store_dwordx4 v[152:153], v[124:127], off
	global_store_dwordx4 v[152:153], v[120:123], off offset:16
.LBB0_1327:
	s_or_b64 exec, exec, s[12:13]
	v_ashrrev_i32_e32 v149, 31, v148
	v_lshlrev_b64 v[150:151], 12, v[148:149]
	v_lshl_add_u64 v[150:151], s[84:85], 0, v[150:151]
	v_cvt_pk_bf16_f32 v156, v124, v125
	v_cvt_pk_bf16_f32 v157, v126, v127
	v_cvt_pk_bf16_f32 v158, v120, v121
	v_cvt_pk_bf16_f32 v159, v122, v123
	v_lshl_add_u64 v[150:151], v[146:147], 1, v[150:151]
	global_store_dwordx4 v[150:151], v[156:159], off
	s_nop 0
	v_pk_add_f32 v[118:119], v[118:119], v[182:183]
	v_pk_add_f32 v[116:117], v[116:117], v[180:181]
	v_pk_add_f32 v[114:115], v[114:115], v[186:187]
	v_pk_add_f32 v[112:113], v[112:113], v[184:185]
	v_add_u32_e32 v220, 48, v148
	v_add_u32_e32 v221, 0x3ff0, v220
	v_lshrrev_b32_e32 v221, 15, v221
	v_mul_u32_u24_e32 v224, 0x4010, v221
	v_sub_u32_e32 v224, v220, v224
	v_lshlrev_b32_e32 v225, 4, v221
	v_cmp_gt_u32_e64 s[12:13], 16, v224
	v_add_u32_e32 v224, v224, v225
	v_sub_u32_e32 v220, v220, v225
	v_subrev_u32_e32 v220, 16, v220
	v_mov_b32_e32 v222, s92
	v_mov_b32_e32 v223, s93
	v_cndmask_b32_e64 v220, v220, v224, s[12:13]
	v_mov_b32_e32 v224, s64
	v_mov_b32_e32 v225, s65
	v_cndmask_b32_e64 v222, v222, v224, s[12:13]
	v_cndmask_b32_e64 v223, v223, v225, s[12:13]
	v_mov_b32_e32 v221, 0
	v_lshlrev_b64 v[220:221], 13, v[220:221]
	v_lshl_add_u64 v[220:221], v[220:221], 0, v[222:223]
	v_lshl_add_u64 v[220:221], v[226:227], 2, v[220:221]
	global_load_dwordx4 v[172:175], v[220:221], off
	global_load_dwordx4 v[176:179], v[220:221], off offset:16
	global_load_dwordx4 v[180:183], v[220:221], off offset:512
	global_load_dwordx4 v[184:187], v[220:221], off offset:528
	s_and_saveexec_b64 s[12:13], s[0:1]
	s_cbranch_execz .LBB0_1329
	global_store_dwordx4 v[152:153], v[116:119], off offset:512
	global_store_dwordx4 v[152:153], v[112:115], off offset:528

; __device__ __forceinline__ unsigned cvt_pk_bf16(float lo, float hi) { f32x2_t v = {lo, hi}; bf16x2_t b = __builtin_convertvector(v, bf16x2_t); return __builtin_bit_cast(unsigned, b); }
;     __device__ __forceinline__ void operator()(f32x4 (&acc)[2][2][4][2], const Unit& u, int wr, int wc, int fr, int fq) const {
;     ...
;                     const int col0 = u.pn * BM + wc * 32 + 8 * fq;
; #pragma unroll
;                     for (int bj = 0; bj < 2; ++bj) {
;                         const int col = col0 + bj * HALF;
;                         const f32x4 v0 = *(const f32x4*)(sp + col) + acc[ai][bj][m][0], v1 = *(const f32x4*)(sp + col + 4) + acc[ai][bj][m][1];
;                         if (dp) { *(f32x4*)(dp + col) = v0; *(f32x4*)(dp + col + 4) = v1; }
;                         if (hb) { u32x4 w; w.x = cvt_pk_bf16(v0[0], v0[1]); w.y = cvt_pk_bf16(v0[2], v0[3]); w.z = cvt_pk_bf16(v1[0], v1[1]); w.w = cvt_pk_bf16(v1[2], v1[3]); *(u32x4*)(hb + (size_t)g * DM + col) = w; }
;                         ss += (v0[0] * v0[0] + v0[1] * v0[1]) + (v0[2] * v0[2] + v0[3] * v0[3]) + (v1[0] * v1[0] + v1[1] * v1[1]) + (v1[2] * v1[2] + v1[3] * v1[3]);
.LBB0_1341:
	s_or_b64 exec, exec, s[0:1]
	v_lshlrev_b64 v[114:115], 13, v[114:115]
	v_lshl_add_u64 v[114:115], v[116:117], 0, v[114:115]
	v_ashrrev_i32_e32 v147, 31, v146
	v_lshl_add_u64 v[118:119], v[146:147], 2, v[114:115]
	v_lshlrev_b64 v[120:121], 13, v[120:121]
	v_lshl_add_u64 v[120:121], v[122:123], 0, v[120:121]
	v_cmp_ne_u64_e64 s[0:1], 0, v[122:123]
	s_waitcnt vmcnt(8)
	v_pk_add_f32 v[110:111], v[110:111], v[190:191]
	v_pk_add_f32 v[108:109], v[108:109], v[188:189]
	v_pk_add_f32 v[106:107], v[106:107], v[194:195]
	v_pk_add_f32 v[104:105], v[104:105], v[192:193]
	v_lshl_add_u64 v[116:117], v[146:147], 2, v[120:121]
	s_and_saveexec_b64 s[12:13], s[0:1]
	s_cbranch_execz .LBB0_1343
	global_store_dwordx4 v[116:117], v[108:111], off
	global_store_dwordx4 v[116:117], v[104:107], off offset:16
.LBB0_1343:
	s_or_b64 exec, exec, s[12:13]
	v_ashrrev_i32_e32 v113, 31, v112
	v_lshlrev_b64 v[114:115], 12, v[112:113]
	v_lshl_add_u64 v[114:115], s[84:85], 0, v[114:115]
	v_cvt_pk_bf16_f32 v120, v108, v109
	v_cvt_pk_bf16_f32 v121, v110, v111
	v_cvt_pk_bf16_f32 v122, v104, v105
	v_cvt_pk_bf16_f32 v123, v106, v107
	v_lshl_add_u64 v[114:115], v[146:147], 1, v[114:115]
	global_store_dwordx4 v[114:115], v[120:123], off
	s_nop 0
	v_pk_add_f32 v[102:103], v[102:103], v[198:199]
	v_pk_add_f32 v[100:101], v[100:101], v[196:197]
	v_pk_add_f32 v[98:99], v[98:99], v[202:203]
	v_pk_add_f32 v[96:97], v[96:97], v[200:201]
	v_add_u32_e32 v220, 0x80, v148
	v_add_u32_e32 v221, 0x3ff0, v220
	v_lshrrev_b32_e32 v221, 15, v221
	v_mul_u32_u24_e32 v224, 0x4010, v221
	v_sub_u32_e32 v224, v220, v224
	v_lshlrev_b32_e32 v225, 4, v221
	v_cmp_gt_u32_e64 s[12:13], 16, v224
	v_add_u32_e32 v224, v224, v225
	v_sub_u32_e32 v220, v220, v225
	v_subrev_u32_e32 v220, 16, v220
	v_mov_b32_e32 v222, s92
	v_mov_b32_e32 v223, s93
	v_cndmask_b32_e64 v220, v220, v224, s[12:13]
	v_mov_b32_e32 v224, s64
	v_mov_b32_e32 v225, s65
	v_cndmask_b32_e64 v222, v222, v224, s[12:13]
	v_cndmask_b32_e64 v223, v223, v225, s[12:13]
	v_mov_b32_e32 v221, 0
	v_lshlrev_b64 v[220:221], 13, v[220:221]
	v_lshl_add_u64 v[220:221], v[220:221], 0, v[222:223]
	v_lshl_add_u64 v[220:221], v[226:227], 2, v[220:221]
	global_load_dwordx4 v[188:191], v[220:221], off
	global_load_dwordx4 v[192:195], v[220:221], off offset:16
	global_load_dwordx4 v[196:199], v[220:221], off offset:512
	global_load_dwordx4 v[200:203], v[220:221], off offset:528
	s_and_saveexec_b64 s[12:13], s[0:1]
	s_cbranch_execz .LBB0_1345
	global_store_dwordx4 v[116:117], v[100:103], off offset:512
	global_store_dwordx4 v[116:117], v[96:99], off offset:528

; __device__ __forceinline__ unsigned cvt_pk_bf16(float lo, float hi) { f32x2_t v = {lo, hi}; bf16x2_t b = __builtin_convertvector(v, bf16x2_t); return __builtin_bit_cast(unsigned, b); }
;     __device__ __forceinline__ void operator()(f32x4 (&acc)[2][2][4][2], const Unit& u, int wr, int wc, int fr, int fq) const {
;     ...
;                     const int col0 = u.pn * BM + wc * 32 + 8 * fq;
; #pragma unroll
;                     for (int bj = 0; bj < 2; ++bj) {
;                         const int col = col0 + bj * HALF;
;                         const f32x4 v0 = *(const f32x4*)(sp + col) + acc[ai][bj][m][0], v1 = *(const f32x4*)(sp + col + 4) + acc[ai][bj][m][1];
;                         if (dp) { *(f32x4*)(dp + col) = v0; *(f32x4*)(dp + col + 4) = v1; }
;                         if (hb) { u32x4 w; w.x = cvt_pk_bf16(v0[0], v0[1]); w.y = cvt_pk_bf16(v0[2], v0[3]); w.z = cvt_pk_bf16(v1[0], v1[1]); w.w = cvt_pk_bf16(v1[2], v1[3]); *(u32x4*)(hb + (size_t)g * DM + col) = w; }
;                         ss += (v0[0] * v0[0] + v0[1] * v0[1]) + (v0[2] * v0[2] + v0[3] * v0[3]) + (v1[0] * v1[0] + v1[1] * v1[1]) + (v1[2] * v1[2] + v1[3] * v1[3]);
.LBB0_1357:
	s_or_b64 exec, exec, s[0:1]
	v_lshlrev_b64 v[98:99], 13, v[98:99]
	v_lshl_add_u64 v[98:99], v[100:101], 0, v[98:99]
	v_ashrrev_i32_e32 v147, 31, v146
	v_lshl_add_u64 v[102:103], v[146:147], 2, v[98:99]
	v_lshlrev_b64 v[104:105], 13, v[104:105]
	v_lshl_add_u64 v[104:105], v[106:107], 0, v[104:105]
	v_cmp_ne_u64_e64 s[0:1], 0, v[106:107]
	s_waitcnt vmcnt(8)
	v_pk_add_f32 v[94:95], v[94:95], v[206:207]
	v_pk_add_f32 v[92:93], v[92:93], v[204:205]
	v_pk_add_f32 v[90:91], v[90:91], v[210:211]
	v_pk_add_f32 v[88:89], v[88:89], v[208:209]
	v_lshl_add_u64 v[100:101], v[146:147], 2, v[104:105]
	s_and_saveexec_b64 s[12:13], s[0:1]
	s_cbranch_execz .LBB0_1359
	global_store_dwordx4 v[100:101], v[92:95], off
	global_store_dwordx4 v[100:101], v[88:91], off offset:16
.LBB0_1359:
	s_or_b64 exec, exec, s[12:13]
	v_ashrrev_i32_e32 v97, 31, v96
	v_lshlrev_b64 v[98:99], 12, v[96:97]
	v_lshl_add_u64 v[98:99], s[84:85], 0, v[98:99]
	v_cvt_pk_bf16_f32 v104, v92, v93
	v_cvt_pk_bf16_f32 v105, v94, v95
	v_cvt_pk_bf16_f32 v106, v88, v89
	v_cvt_pk_bf16_f32 v107, v90, v91
	v_lshl_add_u64 v[98:99], v[146:147], 1, v[98:99]
	global_store_dwordx4 v[98:99], v[104:107], off
	s_nop 0
	v_pk_add_f32 v[86:87], v[86:87], v[214:215]
	v_pk_add_f32 v[84:85], v[84:85], v[212:213]
	v_pk_add_f32 v[82:83], v[82:83], v[218:219]
	v_pk_add_f32 v[80:81], v[80:81], v[216:217]
	v_add_u32_e32 v220, 0x90, v148
	v_add_u32_e32 v221, 0x3ff0, v220
	v_lshrrev_b32_e32 v221, 15, v221
	v_mul_u32_u24_e32 v224, 0x4010, v221
	v_sub_u32_e32 v224, v220, v224
	v_lshlrev_b32_e32 v225, 4, v221
	v_cmp_gt_u32_e64 s[12:13], 16, v224
	v_add_u32_e32 v224, v224, v225
	v_sub_u32_e32 v220, v220, v225
	v_subrev_u32_e32 v220, 16, v220
	v_mov_b32_e32 v222, s92
	v_mov_b32_e32 v223, s93
	v_cndmask_b32_e64 v220, v220, v224, s[12:13]
	v_mov_b32_e32 v224, s64
	v_mov_b32_e32 v225, s65
	v_cndmask_b32_e64 v222, v222, v224, s[12:13]
	v_cndmask_b32_e64 v223, v223, v225, s[12:13]
	v_mov_b32_e32 v221, 0
	v_lshlrev_b64 v[220:221], 13, v[220:221]
	v_lshl_add_u64 v[220:221], v[220:221], 0, v[222:223]
	v_lshl_add_u64 v[220:221], v[226:227], 2, v[220:221]
	global_load_dwordx4 v[204:207], v[220:221], off
	global_load_dwordx4 v[208:211], v[220:221], off offset:16
	global_load_dwordx4 v[212:215], v[220:221], off offset:512
	global_load_dwordx4 v[216:219], v[220:221], off offset:528
	s_and_saveexec_b64 s[12:13], s[0:1]
	s_cbranch_execz .LBB0_1361
	global_store_dwordx4 v[100:101], v[84:87], off offset:512
	global_store_dwordx4 v[100:101], v[80:83], off offset:528

; __device__ __forceinline__ unsigned cvt_pk_bf16(float lo, float hi) { f32x2_t v = {lo, hi}; bf16x2_t b = __builtin_convertvector(v, bf16x2_t); return __builtin_bit_cast(unsigned, b); }
;     __device__ __forceinline__ void operator()(f32x4 (&acc)[2][2][4][2], const Unit& u, int wr, int wc, int fr, int fq) const {
;     ...
;                     const int col0 = u.pn * BM + wc * 32 + 8 * fq;
; #pragma unroll
;                     for (int bj = 0; bj < 2; ++bj) {
;                         const int col = col0 + bj * HALF;
;                         const f32x4 v0 = *(const f32x4*)(sp + col) + acc[ai][bj][m][0], v1 = *(const f32x4*)(sp + col + 4) + acc[ai][bj][m][1];
;                         if (dp) { *(f32x4*)(dp + col) = v0; *(f32x4*)(dp + col + 4) = v1; }
;                         if (hb) { u32x4 w; w.x = cvt_pk_bf16(v0[0], v0[1]); w.y = cvt_pk_bf16(v0[2], v0[3]); w.z = cvt_pk_bf16(v1[0], v1[1]); w.w = cvt_pk_bf16(v1[2], v1[3]); *(u32x4*)(hb + (size_t)g * DM + col) = w; }
;                         ss += (v0[0] * v0[0] + v0[1] * v0[1]) + (v0[2] * v0[2] + v0[3] * v0[3]) + (v1[0] * v1[0] + v1[1] * v1[1]) + (v1[2] * v1[2] + v1[3] * v1[3]);
.LBB0_1373:
	s_or_b64 exec, exec, s[0:1]
	v_lshlrev_b64 v[82:83], 13, v[82:83]
	v_lshl_add_u64 v[82:83], v[84:85], 0, v[82:83]
	v_ashrrev_i32_e32 v147, 31, v146
	v_lshl_add_u64 v[86:87], v[146:147], 2, v[82:83]
	v_lshlrev_b64 v[88:89], 13, v[88:89]
	v_lshl_add_u64 v[88:89], v[90:91], 0, v[88:89]
	v_cmp_ne_u64_e64 s[0:1], 0, v[90:91]
	s_waitcnt vmcnt(8)
	v_pk_add_f32 v[78:79], v[78:79], v[174:175]
	v_pk_add_f32 v[76:77], v[76:77], v[172:173]
	v_pk_add_f32 v[74:75], v[74:75], v[178:179]
	v_pk_add_f32 v[72:73], v[72:73], v[176:177]
	v_lshl_add_u64 v[84:85], v[146:147], 2, v[88:89]
	s_and_saveexec_b64 s[12:13], s[0:1]
	s_cbranch_execz .LBB0_1375
	global_store_dwordx4 v[84:85], v[76:79], off
	global_store_dwordx4 v[84:85], v[72:75], off offset:16
.LBB0_1375:
	s_or_b64 exec, exec, s[12:13]
	v_ashrrev_i32_e32 v81, 31, v80
	v_lshlrev_b64 v[82:83], 12, v[80:81]
	v_lshl_add_u64 v[82:83], s[84:85], 0, v[82:83]
	v_cvt_pk_bf16_f32 v88, v76, v77
	v_cvt_pk_bf16_f32 v89, v78, v79
	v_cvt_pk_bf16_f32 v90, v72, v73
	v_cvt_pk_bf16_f32 v91, v74, v75
	v_lshl_add_u64 v[82:83], v[146:147], 1, v[82:83]
	global_store_dwordx4 v[82:83], v[88:91], off
	s_nop 0
	v_pk_add_f32 v[70:71], v[70:71], v[182:183]
	v_pk_add_f32 v[68:69], v[68:69], v[180:181]
	v_pk_add_f32 v[66:67], v[66:67], v[186:187]
	v_pk_add_f32 v[64:65], v[64:65], v[184:185]
	v_add_u32_e32 v220, 0xa0, v148
	v_add_u32_e32 v221, 0x3ff0, v220
	v_lshrrev_b32_e32 v221, 15, v221
	v_mul_u32_u24_e32 v224, 0x4010, v221
	v_sub_u32_e32 v224, v220, v224
	v_lshlrev_b32_e32 v225, 4, v221
	v_cmp_gt_u32_e64 s[12:13], 16, v224
	v_add_u32_e32 v224, v224, v225
	v_sub_u32_e32 v220, v220, v225
	v_subrev_u32_e32 v220, 16, v220
	v_mov_b32_e32 v222, s92
	v_mov_b32_e32 v223, s93
	v_cndmask_b32_e64 v220, v220, v224, s[12:13]
	v_mov_b32_e32 v224, s64
	v_mov_b32_e32 v225, s65
	v_cndmask_b32_e64 v222, v222, v224, s[12:13]
	v_cndmask_b32_e64 v223, v223, v225, s[12:13]
	v_mov_b32_e32 v221, 0
	v_lshlrev_b64 v[220:221], 13, v[220:221]
	v_lshl_add_u64 v[220:221], v[220:221], 0, v[222:223]
	v_lshl_add_u64 v[220:221], v[226:227], 2, v[220:221]
	global_load_dwordx4 v[172:175], v[220:221], off
	global_load_dwordx4 v[176:179], v[220:221], off offset:16
	global_load_dwordx4 v[180:183], v[220:221], off offset:512
	global_load_dwordx4 v[184:187], v[220:221], off offset:528
	s_and_saveexec_b64 s[12:13], s[0:1]
	s_cbranch_execz .LBB0_1377
	global_store_dwordx4 v[84:85], v[68:71], off offset:512
	global_store_dwordx4 v[84:85], v[64:67], off offset:528

; __device__ __forceinline__ unsigned cvt_pk_bf16(float lo, float hi) { f32x2_t v = {lo, hi}; bf16x2_t b = __builtin_convertvector(v, bf16x2_t); return __builtin_bit_cast(unsigned, b); }
;     __device__ __forceinline__ void operator()(f32x4 (&acc)[2][2][4][2], const Unit& u, int wr, int wc, int fr, int fq) const {
;     ...
;                     const int col0 = u.pn * BM + wc * 32 + 8 * fq;
; #pragma unroll
;                     for (int bj = 0; bj < 2; ++bj) {
;                         const int col = col0 + bj * HALF;
;                         const f32x4 v0 = *(const f32x4*)(sp + col) + acc[ai][bj][m][0], v1 = *(const f32x4*)(sp + col + 4) + acc[ai][bj][m][1];
;                         if (dp) { *(f32x4*)(dp + col) = v0; *(f32x4*)(dp + col + 4) = v1; }
;                         if (hb) { u32x4 w; w.x = cvt_pk_bf16(v0[0], v0[1]); w.y = cvt_pk_bf16(v0[2], v0[3]); w.z = cvt_pk_bf16(v1[0], v1[1]); w.w = cvt_pk_bf16(v1[2], v1[3]); *(u32x4*)(hb + (size_t)g * DM + col) = w; }
;                         ss += (v0[0] * v0[0] + v0[1] * v0[1]) + (v0[2] * v0[2] + v0[3] * v0[3]) + (v1[0] * v1[0] + v1[1] * v1[1]) + (v1[2] * v1[2] + v1[3] * v1[3]);
.LBB0_1389:
	s_or_b64 exec, exec, s[0:1]
	v_lshlrev_b64 v[66:67], 13, v[66:67]
	v_lshl_add_u64 v[66:67], v[68:69], 0, v[66:67]
	v_ashrrev_i32_e32 v147, 31, v146
	v_lshl_add_u64 v[70:71], v[146:147], 2, v[66:67]
	v_lshlrev_b64 v[72:73], 13, v[72:73]
	v_lshl_add_u64 v[72:73], v[74:75], 0, v[72:73]
	v_cmp_ne_u64_e64 s[0:1], 0, v[74:75]
	s_waitcnt vmcnt(8)
	v_pk_add_f32 v[62:63], v[62:63], v[190:191]
	v_pk_add_f32 v[60:61], v[60:61], v[188:189]
	v_pk_add_f32 v[58:59], v[58:59], v[194:195]
	v_pk_add_f32 v[56:57], v[56:57], v[192:193]
	v_lshl_add_u64 v[68:69], v[146:147], 2, v[72:73]
	s_and_saveexec_b64 s[12:13], s[0:1]
	s_cbranch_execz .LBB0_1391
	global_store_dwordx4 v[68:69], v[60:63], off
	global_store_dwordx4 v[68:69], v[56:59], off offset:16
.LBB0_1391:
	s_or_b64 exec, exec, s[12:13]
	v_ashrrev_i32_e32 v65, 31, v64
	v_lshlrev_b64 v[66:67], 12, v[64:65]
	v_lshl_add_u64 v[66:67], s[84:85], 0, v[66:67]
	v_cvt_pk_bf16_f32 v72, v60, v61
	v_cvt_pk_bf16_f32 v73, v62, v63
	v_cvt_pk_bf16_f32 v74, v56, v57
	v_cvt_pk_bf16_f32 v75, v58, v59
	v_lshl_add_u64 v[66:67], v[146:147], 1, v[66:67]
	global_store_dwordx4 v[66:67], v[72:75], off
	s_nop 0
	v_pk_add_f32 v[54:55], v[54:55], v[198:199]
	v_pk_add_f32 v[52:53], v[52:53], v[196:197]
	v_pk_add_f32 v[50:51], v[50:51], v[202:203]
	v_pk_add_f32 v[48:49], v[48:49], v[200:201]
	v_add_u32_e32 v220, 0xb0, v148
	v_add_u32_e32 v221, 0x3ff0, v220
	v_lshrrev_b32_e32 v221, 15, v221
	v_mul_u32_u24_e32 v224, 0x4010, v221
	v_sub_u32_e32 v224, v220, v224
	v_lshlrev_b32_e32 v225, 4, v221
	v_cmp_gt_u32_e64 s[12:13], 16, v224
	v_add_u32_e32 v224, v224, v225
	v_sub_u32_e32 v220, v220, v225
	v_subrev_u32_e32 v220, 16, v220
	v_mov_b32_e32 v222, s92
	v_mov_b32_e32 v223, s93
	v_cndmask_b32_e64 v220, v220, v224, s[12:13]
	v_mov_b32_e32 v224, s64
	v_mov_b32_e32 v225, s65
	v_cndmask_b32_e64 v222, v222, v224, s[12:13]
	v_cndmask_b32_e64 v223, v223, v225, s[12:13]
	v_mov_b32_e32 v221, 0
	v_lshlrev_b64 v[220:221], 13, v[220:221]
	v_lshl_add_u64 v[220:221], v[220:221], 0, v[222:223]
	v_lshl_add_u64 v[220:221], v[226:227], 2, v[220:221]
	global_load_dwordx4 v[188:191], v[220:221], off
	global_load_dwordx4 v[192:195], v[220:221], off offset:16
	global_load_dwordx4 v[196:199], v[220:221], off offset:512
	global_load_dwordx4 v[200:203], v[220:221], off offset:528
	s_and_saveexec_b64 s[12:13], s[0:1]
	s_cbranch_execz .LBB0_1393
	global_store_dwordx4 v[68:69], v[52:55], off offset:512
	global_store_dwordx4 v[68:69], v[48:51], off offset:528

; __device__ __forceinline__ unsigned cvt_pk_bf16(float lo, float hi) { f32x2_t v = {lo, hi}; bf16x2_t b = __builtin_convertvector(v, bf16x2_t); return __builtin_bit_cast(unsigned, b); }
;     __device__ __forceinline__ void operator()(f32x4 (&acc)[2][2][4][2], const Unit& u, int wr, int wc, int fr, int fq) const {
;     ...
;                     const int col0 = u.pn * BM + wc * 32 + 8 * fq;
; #pragma unroll
;                     for (int bj = 0; bj < 2; ++bj) {
;                         const int col = col0 + bj * HALF;
;                         const f32x4 v0 = *(const f32x4*)(sp + col) + acc[ai][bj][m][0], v1 = *(const f32x4*)(sp + col + 4) + acc[ai][bj][m][1];
;                         if (dp) { *(f32x4*)(dp + col) = v0; *(f32x4*)(dp + col + 4) = v1; }
;                         if (hb) { u32x4 w; w.x = cvt_pk_bf16(v0[0], v0[1]); w.y = cvt_pk_bf16(v0[2], v0[3]); w.z = cvt_pk_bf16(v1[0], v1[1]); w.w = cvt_pk_bf16(v1[2], v1[3]); *(u32x4*)(hb + (size_t)g * DM + col) = w; }
;                         ss += (v0[0] * v0[0] + v0[1] * v0[1]) + (v0[2] * v0[2] + v0[3] * v0[3]) + (v1[0] * v1[0] + v1[1] * v1[1]) + (v1[2] * v1[2] + v1[3] * v1[3]);
.LBB0_1405:
	s_or_b64 exec, exec, s[0:1]
	v_lshlrev_b64 v[50:51], 13, v[50:51]
	v_lshl_add_u64 v[50:51], v[52:53], 0, v[50:51]
	v_ashrrev_i32_e32 v147, 31, v146
	v_lshl_add_u64 v[54:55], v[146:147], 2, v[50:51]
	v_lshlrev_b64 v[56:57], 13, v[56:57]
	v_lshl_add_u64 v[56:57], v[58:59], 0, v[56:57]
	v_cmp_ne_u64_e64 s[0:1], 0, v[58:59]
	s_waitcnt vmcnt(8)
	v_pk_add_f32 v[46:47], v[46:47], v[206:207]
	v_pk_add_f32 v[44:45], v[44:45], v[204:205]
	v_pk_add_f32 v[42:43], v[42:43], v[210:211]
	v_pk_add_f32 v[40:41], v[40:41], v[208:209]
	v_lshl_add_u64 v[52:53], v[146:147], 2, v[56:57]
	s_and_saveexec_b64 s[12:13], s[0:1]
	s_cbranch_execz .LBB0_1407
	global_store_dwordx4 v[52:53], v[44:47], off
	global_store_dwordx4 v[52:53], v[40:43], off offset:16
.LBB0_1407:
	s_or_b64 exec, exec, s[12:13]
	v_ashrrev_i32_e32 v49, 31, v48
	v_lshlrev_b64 v[50:51], 12, v[48:49]
	v_lshl_add_u64 v[50:51], s[84:85], 0, v[50:51]
	v_cvt_pk_bf16_f32 v56, v44, v45
	v_cvt_pk_bf16_f32 v57, v46, v47
	v_cvt_pk_bf16_f32 v58, v40, v41
	v_cvt_pk_bf16_f32 v59, v42, v43
	v_lshl_add_u64 v[50:51], v[146:147], 1, v[50:51]
	global_store_dwordx4 v[50:51], v[56:59], off
	s_nop 0
	v_pk_add_f32 v[38:39], v[38:39], v[214:215]
	v_pk_add_f32 v[36:37], v[36:37], v[212:213]
	v_pk_add_f32 v[34:35], v[34:35], v[218:219]
	v_pk_add_f32 v[32:33], v[32:33], v[216:217]
	s_and_saveexec_b64 s[12:13], s[0:1]
	s_cbranch_execz .LBB0_1409
	global_store_dwordx4 v[52:53], v[36:39], off offset:512
	global_store_dwordx4 v[52:53], v[32:35], off offset:528

; __device__ __forceinline__ unsigned cvt_pk_bf16(float lo, float hi) { f32x2_t v = {lo, hi}; bf16x2_t b = __builtin_convertvector(v, bf16x2_t); return __builtin_bit_cast(unsigned, b); }
;     __device__ __forceinline__ void operator()(f32x4 (&acc)[2][2][4][2], const Unit& u, int wr, int wc, int fr, int fq) const {
;     ...
;                     const int col0 = u.pn * BM + wc * 32 + 8 * fq;
; #pragma unroll
;                     for (int bj = 0; bj < 2; ++bj) {
;                         const int col = col0 + bj * HALF;
;                         const f32x4 v0 = *(const f32x4*)(sp + col) + acc[ai][bj][m][0], v1 = *(const f32x4*)(sp + col + 4) + acc[ai][bj][m][1];
;                         if (dp) { *(f32x4*)(dp + col) = v0; *(f32x4*)(dp + col + 4) = v1; }
;                         if (hb) { u32x4 w; w.x = cvt_pk_bf16(v0[0], v0[1]); w.y = cvt_pk_bf16(v0[2], v0[3]); w.z = cvt_pk_bf16(v1[0], v1[1]); w.w = cvt_pk_bf16(v1[2], v1[3]); *(u32x4*)(hb + (size_t)g * DM + col) = w; }
;                         ss += (v0[0] * v0[0] + v0[1] * v0[1]) + (v0[2] * v0[2] + v0[3] * v0[3]) + (v1[0] * v1[0] + v1[1] * v1[1]) + (v1[2] * v1[2] + v1[3] * v1[3]);
.LBB0_1421:
	s_or_b64 exec, exec, s[0:1]
	v_lshlrev_b64 v[34:35], 13, v[34:35]
	v_lshl_add_u64 v[34:35], v[36:37], 0, v[34:35]
	v_ashrrev_i32_e32 v147, 31, v146
	v_lshl_add_u64 v[38:39], v[146:147], 2, v[34:35]
	v_lshlrev_b64 v[40:41], 13, v[40:41]
	v_lshl_add_u64 v[40:41], v[42:43], 0, v[40:41]
	v_cmp_ne_u64_e64 s[0:1], 0, v[42:43]
	s_waitcnt vmcnt(4)
	v_pk_add_f32 v[30:31], v[30:31], v[174:175]
	v_pk_add_f32 v[28:29], v[28:29], v[172:173]
	v_pk_add_f32 v[26:27], v[26:27], v[178:179]
	v_pk_add_f32 v[24:25], v[24:25], v[176:177]
	v_lshl_add_u64 v[36:37], v[146:147], 2, v[40:41]
	s_and_saveexec_b64 s[12:13], s[0:1]
	s_cbranch_execz .LBB0_1423
	global_store_dwordx4 v[36:37], v[28:31], off
	global_store_dwordx4 v[36:37], v[24:27], off offset:16
.LBB0_1423:
	s_or_b64 exec, exec, s[12:13]
	v_ashrrev_i32_e32 v33, 31, v32
	v_lshlrev_b64 v[34:35], 12, v[32:33]
	v_lshl_add_u64 v[34:35], s[84:85], 0, v[34:35]
	v_cvt_pk_bf16_f32 v40, v28, v29
	v_cvt_pk_bf16_f32 v41, v30, v31
	v_cvt_pk_bf16_f32 v42, v24, v25
	v_cvt_pk_bf16_f32 v43, v26, v27
	v_lshl_add_u64 v[34:35], v[146:147], 1, v[34:35]
	global_store_dwordx4 v[34:35], v[40:43], off
	s_nop 0
	v_pk_add_f32 v[22:23], v[22:23], v[182:183]
	v_pk_add_f32 v[20:21], v[20:21], v[180:181]
	v_pk_add_f32 v[18:19], v[18:19], v[186:187]
	v_pk_add_f32 v[16:17], v[16:17], v[184:185]
	s_and_saveexec_b64 s[12:13], s[0:1]
	s_cbranch_execz .LBB0_1425
	global_store_dwordx4 v[36:37], v[20:23], off offset:512
	global_store_dwordx4 v[36:37], v[16:19], off offset:528

; __device__ __forceinline__ unsigned cvt_pk_bf16(float lo, float hi) { f32x2_t v = {lo, hi}; bf16x2_t b = __builtin_convertvector(v, bf16x2_t); return __builtin_bit_cast(unsigned, b); }
;     __device__ __forceinline__ void operator()(f32x4 (&acc)[2][2][4][2], const Unit& u, int wr, int wc, int fr, int fq) const {
;     ...
;                     const int col0 = u.pn * BM + wc * 32 + 8 * fq;
; #pragma unroll
;                     for (int bj = 0; bj < 2; ++bj) {
;                         const int col = col0 + bj * HALF;
;                         const f32x4 v0 = *(const f32x4*)(sp + col) + acc[ai][bj][m][0], v1 = *(const f32x4*)(sp + col + 4) + acc[ai][bj][m][1];
;                         if (dp) { *(f32x4*)(dp + col) = v0; *(f32x4*)(dp + col + 4) = v1; }
;                         if (hb) { u32x4 w; w.x = cvt_pk_bf16(v0[0], v0[1]); w.y = cvt_pk_bf16(v0[2], v0[3]); w.z = cvt_pk_bf16(v1[0], v1[1]); w.w = cvt_pk_bf16(v1[2], v1[3]); *(u32x4*)(hb + (size_t)g * DM + col) = w; }
;                         ss += (v0[0] * v0[0] + v0[1] * v0[1]) + (v0[2] * v0[2] + v0[3] * v0[3]) + (v1[0] * v1[0] + v1[1] * v1[1]) + (v1[2] * v1[2] + v1[3] * v1[3]);
.LBB0_1437:
	s_or_b64 exec, exec, s[0:1]
	v_lshlrev_b64 v[18:19], 13, v[18:19]
	v_lshl_add_u64 v[18:19], v[20:21], 0, v[18:19]
	v_ashrrev_i32_e32 v147, 31, v146
	v_lshl_add_u64 v[22:23], v[146:147], 2, v[18:19]
	v_lshlrev_b64 v[24:25], 13, v[24:25]
	v_lshl_add_u64 v[24:25], v[26:27], 0, v[24:25]
	v_cmp_ne_u64_e64 s[0:1], 0, v[26:27]
	s_waitcnt vmcnt(0)
	v_pk_add_f32 v[14:15], v[14:15], v[190:191]
	v_pk_add_f32 v[12:13], v[12:13], v[188:189]
	v_pk_add_f32 v[10:11], v[10:11], v[194:195]
	v_pk_add_f32 v[8:9], v[8:9], v[192:193]
	v_lshl_add_u64 v[20:21], v[146:147], 2, v[24:25]
	s_and_saveexec_b64 s[12:13], s[0:1]
	s_cbranch_execz .LBB0_1439
	global_store_dwordx4 v[20:21], v[12:15], off
	global_store_dwordx4 v[20:21], v[8:11], off offset:16
.LBB0_1439:
	s_or_b64 exec, exec, s[12:13]
	v_ashrrev_i32_e32 v17, 31, v16
	v_lshlrev_b64 v[18:19], 12, v[16:17]
	v_lshl_add_u64 v[18:19], s[84:85], 0, v[18:19]
	v_cvt_pk_bf16_f32 v24, v12, v13
	v_cvt_pk_bf16_f32 v25, v14, v15
	v_cvt_pk_bf16_f32 v26, v8, v9
	v_cvt_pk_bf16_f32 v27, v10, v11
	v_lshl_add_u64 v[18:19], v[146:147], 1, v[18:19]
	global_store_dwordx4 v[18:19], v[24:27], off
	s_nop 0
	v_pk_add_f32 v[6:7], v[6:7], v[198:199]
	v_pk_add_f32 v[4:5], v[4:5], v[196:197]
	v_pk_add_f32 v[2:3], v[2:3], v[202:203]
	v_pk_add_f32 v[0:1], v[0:1], v[200:201]
	s_and_saveexec_b64 s[12:13], s[0:1]
	s_cbranch_execz .LBB0_1441
	global_store_dwordx4 v[20:21], v[4:7], off offset:512
	global_store_dwordx4 v[20:21], v[0:3], off offset:528

; __device__ __forceinline__ unsigned cvt_pk_bf16(float lo, float hi) { f32x2_t v = {lo, hi}; bf16x2_t b = __builtin_convertvector(v, bf16x2_t); return __builtin_bit_cast(unsigned, b); }
;     __device__ __forceinline__ void operator()(f32x4 (&acc)[2][2][4][2], const Unit& u, int wr, int wc, int fr, int fq) const {
;     ...
;         for (int ai = 0; ai < 2; ++ai)
; #pragma unroll
;             for (int m = 0; m < 4; ++m) {
;                 const int g = u.pm * BM + ai * HALF + wr * 64 + m * 16 + fr; const bool ok = g < M;
;                 const float rs = ok ? rsqrtf(ssq[g] * (1.0f / DM) + EPS) : 0.f;
;                 bf16_t* rowp = O + (size_t)g * ldc + u.pn * BM + wc * 32 + 8 * fq;
; #pragma unroll
;                 for (int bj = 0; bj < 2; ++bj) {
;                     f32x4 v0 = acc[ai][bj][m][0], v1 = acc[ai][bj][m][1]; u32x4 w;
;                     if (ok) { w.x = cvt_pk_bf16(v0[0] * rs, v0[1] * rs); w.y = cvt_pk_bf16(v0[2] * rs, v0[3] * rs); w.z = cvt_pk_bf16(v1[0] * rs, v1[1] * rs); w.w = cvt_pk_bf16(v1[2] * rs, v1[3] * rs); }
;                     else { w = (u32x4){0u, 0u, 0u, 0u}; }
;                     *(u32x4*)(rowp + bj * HALF) = w;
.LBB0_1522:
	v_lshl_add_u32 v154, s0, 8, v157
	v_mov_b32_e32 v164, v154
	v_mov_b32_e32 v165, 0
	v_lshl_add_u64 v[164:165], v[164:165], 2, s[14:15]
	global_load_dword v166, v[164:165], off
	global_load_dword v167, v[164:165], off offset:64
	global_load_dword v168, v[164:165], off offset:128
	global_load_dword v169, v[164:165], off offset:192
	global_load_dword v170, v[164:165], off offset:512
	global_load_dword v171, v[164:165], off offset:576
	global_load_dword v172, v[164:165], off offset:640
	global_load_dword v173, v[164:165], off offset:704
	s_waitcnt vmcnt(0)
	v_cmp_gt_i32_e32 vcc, s55, v154
	v_cmp_lt_i32_e64 s[0:1], s56, v154
	s_and_saveexec_b64 s[30:31], s[0:1]
	s_xor_b64 s[0:1], exec, s[30:31]
	v_mov_b32_e32 v155, v145
	s_or_saveexec_b64 s[30:31], s[0:1]
	v_mov_b32_e32 v128, 0
	v_mov_b32_e32 v156, 0
	s_xor_b64 exec, exec, s[30:31]
	s_cbranch_execz .LBB0_1526
	v_ashrrev_i32_e32 v155, 31, v154
	v_lshl_add_u64 v[130:131], v[154:155], 2, s[14:15]
	v_mov_b32_e32 v129, v166
	v_fmamk_f32 v129, v129, 0x3a000000, v162
	v_mul_f32_e32 v130, 0x4b800000, v129
	v_cmp_gt_f32_e64 s[0:1], s57, v129
	s_nop 1
	v_cndmask_b32_e64 v129, v129, v130, s[0:1]
	v_rsq_f32_e32 v129, v129
	s_nop 0
	v_mul_f32_e32 v130, 0x45800000, v129
	v_cndmask_b32_e64 v156, v129, v130, s[0:1]

; __device__ __forceinline__ unsigned cvt_pk_bf16(float lo, float hi) { f32x2_t v = {lo, hi}; bf16x2_t b = __builtin_convertvector(v, bf16x2_t); return __builtin_bit_cast(unsigned, b); }
;     __device__ __forceinline__ void operator()(f32x4 (&acc)[2][2][4][2], const Unit& u, int wr, int wc, int fr, int fq) const {
;     ...
;             for (int m = 0; m < 4; ++m) {
;                 const int g = u.pm * BM + ai * HALF + wr * 64 + m * 16 + fr; const bool ok = g < M;
;                 const float rs = ok ? rsqrtf(ssq[g] * (1.0f / DM) + EPS) : 0.f;
;                 bf16_t* rowp = O + (size_t)g * ldc + u.pn * BM + wc * 32 + 8 * fq;
; #pragma unroll
;                 for (int bj = 0; bj < 2; ++bj) {
;                     f32x4 v0 = acc[ai][bj][m][0], v1 = acc[ai][bj][m][1]; u32x4 w;
;                     if (ok) { w.x = cvt_pk_bf16(v0[0] * rs, v0[1] * rs); w.y = cvt_pk_bf16(v0[2] * rs, v0[3] * rs); w.z = cvt_pk_bf16(v1[0] * rs, v1[1] * rs); w.w = cvt_pk_bf16(v1[2] * rs, v1[3] * rs); }
;                     else { w = (u32x4){0u, 0u, 0u, 0u}; }
;                     *(u32x4*)(rowp + bj * HALF) = w;
.LBB0_1528:
	s_or_b64 exec, exec, s[0:1]
	v_mov_b64_e32 v[112:113], s[70:71]
	v_mad_u64_u32 v[112:113], s[0:1], v154, s58, v[112:113]
	v_mov_b32_e32 v114, v113
	s_lshl_b32 s28, s28, 8
	v_mad_u64_u32 v[114:115], s[0:1], v155, s58, v[114:115]
	s_ashr_i32 s29, s28, 31
	v_mov_b32_e32 v113, v114
	v_lshl_add_u64 v[112:113], s[28:29], 1, v[112:113]
	v_lshl_add_u64 v[112:113], v[112:113], 0, s[10:11]
	v_or_b32_e32 v120, 16, v154
	v_lshl_add_u64 v[112:113], v[112:113], 0, v[144:145]
	v_cmp_gt_i32_e32 vcc, s55, v120
	v_cmp_lt_i32_e64 s[0:1], s56, v120
	global_store_dwordx4 v[112:113], v[128:131], off
	global_store_dwordx4 v[112:113], v[132:135], off offset:256
	s_and_saveexec_b64 s[30:31], s[0:1]
	s_xor_b64 s[0:1], exec, s[30:31]
	v_mov_b32_e32 v121, v145
	s_or_saveexec_b64 s[30:31], s[0:1]
	v_mov_b32_e32 v112, 0
	v_mov_b32_e32 v122, 0
	s_xor_b64 exec, exec, s[30:31]
	s_cbranch_execz .LBB0_1532
	v_ashrrev_i32_e32 v121, 31, v120
	v_lshl_add_u64 v[114:115], v[120:121], 2, s[14:15]
	v_mov_b32_e32 v113, v167
	v_fmamk_f32 v113, v113, 0x3a000000, v162
	v_mul_f32_e32 v114, 0x4b800000, v113
	v_cmp_gt_f32_e64 s[0:1], s57, v113
	s_nop 1
	v_cndmask_b32_e64 v113, v113, v114, s[0:1]
	v_rsq_f32_e32 v113, v113
	s_nop 0
	v_mul_f32_e32 v114, 0x45800000, v113
	v_cndmask_b32_e64 v122, v113, v114, s[0:1]

; __device__ __forceinline__ unsigned cvt_pk_bf16(float lo, float hi) { f32x2_t v = {lo, hi}; bf16x2_t b = __builtin_convertvector(v, bf16x2_t); return __builtin_bit_cast(unsigned, b); }
;     __device__ __forceinline__ void operator()(f32x4 (&acc)[2][2][4][2], const Unit& u, int wr, int wc, int fr, int fq) const {
;     ...
;             for (int m = 0; m < 4; ++m) {
;                 const int g = u.pm * BM + ai * HALF + wr * 64 + m * 16 + fr; const bool ok = g < M;
;                 const float rs = ok ? rsqrtf(ssq[g] * (1.0f / DM) + EPS) : 0.f;
;                 bf16_t* rowp = O + (size_t)g * ldc + u.pn * BM + wc * 32 + 8 * fq;
; #pragma unroll
;                 for (int bj = 0; bj < 2; ++bj) {
;                     f32x4 v0 = acc[ai][bj][m][0], v1 = acc[ai][bj][m][1]; u32x4 w;
;                     if (ok) { w.x = cvt_pk_bf16(v0[0] * rs, v0[1] * rs); w.y = cvt_pk_bf16(v0[2] * rs, v0[3] * rs); w.z = cvt_pk_bf16(v1[0] * rs, v1[1] * rs); w.w = cvt_pk_bf16(v1[2] * rs, v1[3] * rs); }
;                     else { w = (u32x4){0u, 0u, 0u, 0u}; }
;                     *(u32x4*)(rowp + bj * HALF) = w;
.LBB0_1534:
	s_or_b64 exec, exec, s[0:1]
	v_mov_b64_e32 v[96:97], s[70:71]
	v_mad_u64_u32 v[96:97], s[0:1], v120, s58, v[96:97]
	v_mov_b32_e32 v98, v97
	v_mad_u64_u32 v[98:99], s[0:1], v121, s58, v[98:99]
	v_mov_b32_e32 v97, v98
	v_lshl_add_u64 v[96:97], s[28:29], 1, v[96:97]
	v_lshl_add_u64 v[96:97], v[96:97], 0, s[10:11]
	v_or_b32_e32 v104, 32, v154
	v_lshl_add_u64 v[96:97], v[96:97], 0, v[144:145]
	v_cmp_gt_i32_e32 vcc, s55, v104
	v_cmp_lt_i32_e64 s[0:1], s56, v104
	global_store_dwordx4 v[96:97], v[112:115], off
	global_store_dwordx4 v[96:97], v[116:119], off offset:256
	s_and_saveexec_b64 s[30:31], s[0:1]
	s_xor_b64 s[0:1], exec, s[30:31]
	v_mov_b32_e32 v105, v145
	s_or_saveexec_b64 s[30:31], s[0:1]
	v_mov_b32_e32 v96, 0
	v_mov_b32_e32 v106, 0
	s_xor_b64 exec, exec, s[30:31]
	s_cbranch_execz .LBB0_1538
	v_ashrrev_i32_e32 v105, 31, v104
	v_lshl_add_u64 v[98:99], v[104:105], 2, s[14:15]
	v_mov_b32_e32 v97, v168
	v_fmamk_f32 v97, v97, 0x3a000000, v162
	v_mul_f32_e32 v98, 0x4b800000, v97
	v_cmp_gt_f32_e64 s[0:1], s57, v97
	s_nop 1
	v_cndmask_b32_e64 v97, v97, v98, s[0:1]
	v_rsq_f32_e32 v97, v97
	s_nop 0
	v_mul_f32_e32 v98, 0x45800000, v97
	v_cndmask_b32_e64 v106, v97, v98, s[0:1]

; __device__ __forceinline__ unsigned cvt_pk_bf16(float lo, float hi) { f32x2_t v = {lo, hi}; bf16x2_t b = __builtin_convertvector(v, bf16x2_t); return __builtin_bit_cast(unsigned, b); }
;     __device__ __forceinline__ void operator()(f32x4 (&acc)[2][2][4][2], const Unit& u, int wr, int wc, int fr, int fq) const {
;     ...
;             for (int m = 0; m < 4; ++m) {
;                 const int g = u.pm * BM + ai * HALF + wr * 64 + m * 16 + fr; const bool ok = g < M;
;                 const float rs = ok ? rsqrtf(ssq[g] * (1.0f / DM) + EPS) : 0.f;
;                 bf16_t* rowp = O + (size_t)g * ldc + u.pn * BM + wc * 32 + 8 * fq;
; #pragma unroll
;                 for (int bj = 0; bj < 2; ++bj) {
;                     f32x4 v0 = acc[ai][bj][m][0], v1 = acc[ai][bj][m][1]; u32x4 w;
;                     if (ok) { w.x = cvt_pk_bf16(v0[0] * rs, v0[1] * rs); w.y = cvt_pk_bf16(v0[2] * rs, v0[3] * rs); w.z = cvt_pk_bf16(v1[0] * rs, v1[1] * rs); w.w = cvt_pk_bf16(v1[2] * rs, v1[3] * rs); }
;                     else { w = (u32x4){0u, 0u, 0u, 0u}; }
;                     *(u32x4*)(rowp + bj * HALF) = w;
.LBB0_1540:
	s_or_b64 exec, exec, s[0:1]
	v_mov_b64_e32 v[80:81], s[70:71]
	v_mad_u64_u32 v[80:81], s[0:1], v104, s58, v[80:81]
	v_mov_b32_e32 v82, v81
	v_mad_u64_u32 v[82:83], s[0:1], v105, s58, v[82:83]
	v_mov_b32_e32 v81, v82
	v_lshl_add_u64 v[80:81], s[28:29], 1, v[80:81]
	v_lshl_add_u64 v[80:81], v[80:81], 0, s[10:11]
	v_or_b32_e32 v88, 48, v154
	v_lshl_add_u64 v[80:81], v[80:81], 0, v[144:145]
	v_cmp_gt_i32_e32 vcc, s55, v88
	v_cmp_lt_i32_e64 s[0:1], s56, v88
	global_store_dwordx4 v[80:81], v[96:99], off
	global_store_dwordx4 v[80:81], v[100:103], off offset:256
	s_and_saveexec_b64 s[30:31], s[0:1]
	s_xor_b64 s[0:1], exec, s[30:31]
	v_mov_b32_e32 v89, v145
	s_or_saveexec_b64 s[30:31], s[0:1]
	v_mov_b32_e32 v80, 0
	v_mov_b32_e32 v90, 0
	s_xor_b64 exec, exec, s[30:31]
	s_cbranch_execz .LBB0_1544
	v_ashrrev_i32_e32 v89, 31, v88
	v_lshl_add_u64 v[82:83], v[88:89], 2, s[14:15]
	v_mov_b32_e32 v81, v169
	v_fmamk_f32 v81, v81, 0x3a000000, v162
	v_mul_f32_e32 v82, 0x4b800000, v81
	v_cmp_gt_f32_e64 s[0:1], s57, v81
	s_nop 1
	v_cndmask_b32_e64 v81, v81, v82, s[0:1]
	v_rsq_f32_e32 v81, v81
	s_nop 0
	v_mul_f32_e32 v82, 0x45800000, v81
	v_cndmask_b32_e64 v90, v81, v82, s[0:1]

; __device__ __forceinline__ unsigned cvt_pk_bf16(float lo, float hi) { f32x2_t v = {lo, hi}; bf16x2_t b = __builtin_convertvector(v, bf16x2_t); return __builtin_bit_cast(unsigned, b); }
;     __device__ __forceinline__ void operator()(f32x4 (&acc)[2][2][4][2], const Unit& u, int wr, int wc, int fr, int fq) const {
;     ...
;             for (int m = 0; m < 4; ++m) {
;                 const int g = u.pm * BM + ai * HALF + wr * 64 + m * 16 + fr; const bool ok = g < M;
;                 const float rs = ok ? rsqrtf(ssq[g] * (1.0f / DM) + EPS) : 0.f;
;                 bf16_t* rowp = O + (size_t)g * ldc + u.pn * BM + wc * 32 + 8 * fq;
; #pragma unroll
;                 for (int bj = 0; bj < 2; ++bj) {
;                     f32x4 v0 = acc[ai][bj][m][0], v1 = acc[ai][bj][m][1]; u32x4 w;
;                     if (ok) { w.x = cvt_pk_bf16(v0[0] * rs, v0[1] * rs); w.y = cvt_pk_bf16(v0[2] * rs, v0[3] * rs); w.z = cvt_pk_bf16(v1[0] * rs, v1[1] * rs); w.w = cvt_pk_bf16(v1[2] * rs, v1[3] * rs); }
;                     else { w = (u32x4){0u, 0u, 0u, 0u}; }
;                     *(u32x4*)(rowp + bj * HALF) = w;
.LBB0_1546:
	s_or_b64 exec, exec, s[0:1]
	v_mov_b64_e32 v[64:65], s[70:71]
	v_mad_u64_u32 v[64:65], s[0:1], v88, s58, v[64:65]
	v_mov_b32_e32 v66, v65
	v_mad_u64_u32 v[66:67], s[0:1], v89, s58, v[66:67]
	v_mov_b32_e32 v65, v66
	v_lshl_add_u64 v[64:65], s[28:29], 1, v[64:65]
	v_lshl_add_u64 v[64:65], v[64:65], 0, s[10:11]
	v_add_u32_e32 v72, 0x80, v154
	v_lshl_add_u64 v[64:65], v[64:65], 0, v[144:145]
	v_cmp_gt_i32_e32 vcc, s55, v72
	v_cmp_lt_i32_e64 s[0:1], s56, v72
	global_store_dwordx4 v[64:65], v[80:83], off
	global_store_dwordx4 v[64:65], v[84:87], off offset:256
	s_and_saveexec_b64 s[30:31], s[0:1]
	s_xor_b64 s[0:1], exec, s[30:31]
	v_mov_b32_e32 v73, v145
	s_or_saveexec_b64 s[30:31], s[0:1]
	v_mov_b32_e32 v64, 0
	v_mov_b32_e32 v74, 0
	s_xor_b64 exec, exec, s[30:31]
	s_cbranch_execz .LBB0_1550
	v_ashrrev_i32_e32 v73, 31, v72
	v_lshl_add_u64 v[66:67], v[72:73], 2, s[14:15]
	v_mov_b32_e32 v65, v170
	v_fmamk_f32 v65, v65, 0x3a000000, v162
	v_mul_f32_e32 v66, 0x4b800000, v65
	v_cmp_gt_f32_e64 s[0:1], s57, v65
	s_nop 1
	v_cndmask_b32_e64 v65, v65, v66, s[0:1]
	v_rsq_f32_e32 v65, v65
	s_nop 0
	v_mul_f32_e32 v66, 0x45800000, v65
	v_cndmask_b32_e64 v74, v65, v66, s[0:1]

; __device__ __forceinline__ unsigned cvt_pk_bf16(float lo, float hi) { f32x2_t v = {lo, hi}; bf16x2_t b = __builtin_convertvector(v, bf16x2_t); return __builtin_bit_cast(unsigned, b); }
;     __device__ __forceinline__ void operator()(f32x4 (&acc)[2][2][4][2], const Unit& u, int wr, int wc, int fr, int fq) const {
;     ...
;             for (int m = 0; m < 4; ++m) {
;                 const int g = u.pm * BM + ai * HALF + wr * 64 + m * 16 + fr; const bool ok = g < M;
;                 const float rs = ok ? rsqrtf(ssq[g] * (1.0f / DM) + EPS) : 0.f;
;                 bf16_t* rowp = O + (size_t)g * ldc + u.pn * BM + wc * 32 + 8 * fq;
; #pragma unroll
;                 for (int bj = 0; bj < 2; ++bj) {
;                     f32x4 v0 = acc[ai][bj][m][0], v1 = acc[ai][bj][m][1]; u32x4 w;
;                     if (ok) { w.x = cvt_pk_bf16(v0[0] * rs, v0[1] * rs); w.y = cvt_pk_bf16(v0[2] * rs, v0[3] * rs); w.z = cvt_pk_bf16(v1[0] * rs, v1[1] * rs); w.w = cvt_pk_bf16(v1[2] * rs, v1[3] * rs); }
;                     else { w = (u32x4){0u, 0u, 0u, 0u}; }
;                     *(u32x4*)(rowp + bj * HALF) = w;
.LBB0_1552:
	s_or_b64 exec, exec, s[0:1]
	v_mov_b64_e32 v[48:49], s[70:71]
	v_mad_u64_u32 v[48:49], s[0:1], v72, s58, v[48:49]
	v_mov_b32_e32 v50, v49
	v_mad_u64_u32 v[50:51], s[0:1], v73, s58, v[50:51]
	v_mov_b32_e32 v49, v50
	v_lshl_add_u64 v[48:49], s[28:29], 1, v[48:49]
	v_lshl_add_u64 v[48:49], v[48:49], 0, s[10:11]
	v_add_u32_e32 v56, 0x90, v154
	v_lshl_add_u64 v[48:49], v[48:49], 0, v[144:145]
	v_cmp_gt_i32_e32 vcc, s55, v56
	v_cmp_lt_i32_e64 s[0:1], s56, v56
	global_store_dwordx4 v[48:49], v[64:67], off
	global_store_dwordx4 v[48:49], v[68:71], off offset:256
	s_and_saveexec_b64 s[30:31], s[0:1]
	s_xor_b64 s[0:1], exec, s[30:31]
	v_mov_b32_e32 v57, v145
	s_or_saveexec_b64 s[30:31], s[0:1]
	v_mov_b32_e32 v48, 0
	v_mov_b32_e32 v58, 0
	s_xor_b64 exec, exec, s[30:31]
	s_cbranch_execz .LBB0_1556
	v_ashrrev_i32_e32 v57, 31, v56
	v_lshl_add_u64 v[50:51], v[56:57], 2, s[14:15]
	v_mov_b32_e32 v49, v171
	v_fmamk_f32 v49, v49, 0x3a000000, v162
	v_mul_f32_e32 v50, 0x4b800000, v49
	v_cmp_gt_f32_e64 s[0:1], s57, v49
	s_nop 1
	v_cndmask_b32_e64 v49, v49, v50, s[0:1]
	v_rsq_f32_e32 v49, v49
	s_nop 0
	v_mul_f32_e32 v50, 0x45800000, v49
	v_cndmask_b32_e64 v58, v49, v50, s[0:1]

; __device__ __forceinline__ unsigned cvt_pk_bf16(float lo, float hi) { f32x2_t v = {lo, hi}; bf16x2_t b = __builtin_convertvector(v, bf16x2_t); return __builtin_bit_cast(unsigned, b); }
;     __device__ __forceinline__ void operator()(f32x4 (&acc)[2][2][4][2], const Unit& u, int wr, int wc, int fr, int fq) const {
;     ...
;             for (int m = 0; m < 4; ++m) {
;                 const int g = u.pm * BM + ai * HALF + wr * 64 + m * 16 + fr; const bool ok = g < M;
;                 const float rs = ok ? rsqrtf(ssq[g] * (1.0f / DM) + EPS) : 0.f;
;                 bf16_t* rowp = O + (size_t)g * ldc + u.pn * BM + wc * 32 + 8 * fq;
; #pragma unroll
;                 for (int bj = 0; bj < 2; ++bj) {
;                     f32x4 v0 = acc[ai][bj][m][0], v1 = acc[ai][bj][m][1]; u32x4 w;
;                     if (ok) { w.x = cvt_pk_bf16(v0[0] * rs, v0[1] * rs); w.y = cvt_pk_bf16(v0[2] * rs, v0[3] * rs); w.z = cvt_pk_bf16(v1[0] * rs, v1[1] * rs); w.w = cvt_pk_bf16(v1[2] * rs, v1[3] * rs); }
;                     else { w = (u32x4){0u, 0u, 0u, 0u}; }
;                     *(u32x4*)(rowp + bj * HALF) = w;
.LBB0_1558:
	s_or_b64 exec, exec, s[0:1]
	v_mov_b64_e32 v[32:33], s[70:71]
	v_mad_u64_u32 v[32:33], s[0:1], v56, s58, v[32:33]
	v_mov_b32_e32 v34, v33
	v_mad_u64_u32 v[34:35], s[0:1], v57, s58, v[34:35]
	v_mov_b32_e32 v33, v34
	v_lshl_add_u64 v[32:33], s[28:29], 1, v[32:33]
	v_lshl_add_u64 v[32:33], v[32:33], 0, s[10:11]
	v_add_u32_e32 v40, 0xa0, v154
	v_lshl_add_u64 v[32:33], v[32:33], 0, v[144:145]
	v_cmp_gt_i32_e32 vcc, s55, v40
	v_cmp_lt_i32_e64 s[0:1], s56, v40
	global_store_dwordx4 v[32:33], v[48:51], off
	global_store_dwordx4 v[32:33], v[52:55], off offset:256
	s_and_saveexec_b64 s[30:31], s[0:1]
	s_xor_b64 s[0:1], exec, s[30:31]
	v_mov_b32_e32 v41, v145
	s_or_saveexec_b64 s[30:31], s[0:1]
	v_mov_b32_e32 v32, 0
	v_mov_b32_e32 v42, 0
	s_xor_b64 exec, exec, s[30:31]
	s_cbranch_execz .LBB0_1562
	v_ashrrev_i32_e32 v41, 31, v40
	v_lshl_add_u64 v[34:35], v[40:41], 2, s[14:15]
	v_mov_b32_e32 v33, v172
	v_fmamk_f32 v33, v33, 0x3a000000, v162
	v_mul_f32_e32 v34, 0x4b800000, v33
	v_cmp_gt_f32_e64 s[0:1], s57, v33
	s_nop 1
	v_cndmask_b32_e64 v33, v33, v34, s[0:1]
	v_rsq_f32_e32 v33, v33
	s_nop 0
	v_mul_f32_e32 v34, 0x45800000, v33
	v_cndmask_b32_e64 v42, v33, v34, s[0:1]

; __device__ __forceinline__ unsigned cvt_pk_bf16(float lo, float hi) { f32x2_t v = {lo, hi}; bf16x2_t b = __builtin_convertvector(v, bf16x2_t); return __builtin_bit_cast(unsigned, b); }
;     __device__ __forceinline__ void operator()(f32x4 (&acc)[2][2][4][2], const Unit& u, int wr, int wc, int fr, int fq) const {
;     ...
;             for (int m = 0; m < 4; ++m) {
;                 const int g = u.pm * BM + ai * HALF + wr * 64 + m * 16 + fr; const bool ok = g < M;
;                 const float rs = ok ? rsqrtf(ssq[g] * (1.0f / DM) + EPS) : 0.f;
;                 bf16_t* rowp = O + (size_t)g * ldc + u.pn * BM + wc * 32 + 8 * fq;
; #pragma unroll
;                 for (int bj = 0; bj < 2; ++bj) {
;                     f32x4 v0 = acc[ai][bj][m][0], v1 = acc[ai][bj][m][1]; u32x4 w;
;                     if (ok) { w.x = cvt_pk_bf16(v0[0] * rs, v0[1] * rs); w.y = cvt_pk_bf16(v0[2] * rs, v0[3] * rs); w.z = cvt_pk_bf16(v1[0] * rs, v1[1] * rs); w.w = cvt_pk_bf16(v1[2] * rs, v1[3] * rs); }
;                     else { w = (u32x4){0u, 0u, 0u, 0u}; }
;                     *(u32x4*)(rowp + bj * HALF) = w;
.LBB0_1564:
	s_or_b64 exec, exec, s[0:1]
	v_mov_b64_e32 v[16:17], s[70:71]
	v_mad_u64_u32 v[16:17], s[0:1], v40, s58, v[16:17]
	v_mov_b32_e32 v18, v17
	v_mad_u64_u32 v[18:19], s[0:1], v41, s58, v[18:19]
	v_mov_b32_e32 v17, v18
	v_lshl_add_u64 v[16:17], s[28:29], 1, v[16:17]
	v_lshl_add_u64 v[16:17], v[16:17], 0, s[10:11]
	v_add_u32_e32 v24, 0xb0, v154
	v_lshl_add_u64 v[16:17], v[16:17], 0, v[144:145]
	v_cmp_gt_i32_e32 vcc, s55, v24
	v_cmp_lt_i32_e64 s[0:1], s56, v24
	global_store_dwordx4 v[16:17], v[32:35], off
	global_store_dwordx4 v[16:17], v[36:39], off offset:256
	s_and_saveexec_b64 s[30:31], s[0:1]
	s_xor_b64 s[0:1], exec, s[30:31]
	v_mov_b32_e32 v25, v145
	s_or_saveexec_b64 s[30:31], s[0:1]
	v_mov_b32_e32 v16, 0
	v_mov_b32_e32 v26, 0
	s_xor_b64 exec, exec, s[30:31]
	s_cbranch_execz .LBB0_1568
	v_ashrrev_i32_e32 v25, 31, v24
	v_lshl_add_u64 v[18:19], v[24:25], 2, s[14:15]
	v_mov_b32_e32 v17, v173
	v_fmamk_f32 v17, v17, 0x3a000000, v162
	v_mul_f32_e32 v18, 0x4b800000, v17
	v_cmp_gt_f32_e64 s[0:1], s57, v17
	s_nop 1
	v_cndmask_b32_e64 v17, v17, v18, s[0:1]
	v_rsq_f32_e32 v17, v17
	s_nop 0
	v_mul_f32_e32 v18, 0x45800000, v17
	v_cndmask_b32_e64 v26, v17, v18, s[0:1]

; __device__ __forceinline__ unsigned cvt_pk_bf16(float lo, float hi) { f32x2_t v = {lo, hi}; bf16x2_t b = __builtin_convertvector(v, bf16x2_t); return __builtin_bit_cast(unsigned, b); }
;     __device__ __forceinline__ void operator()(f32x4 (&acc)[2][2][4][2], const Unit& u, int wr, int wc, int fr, int fq) const {
;     ...
;         for (int ai = 0; ai < 2; ++ai)
; #pragma unroll
;             for (int m = 0; m < 4; ++m) {
;                 const int g = u.pm * BM + ai * HALF + wr * 64 + m * 16 + fr; float ss = 0.f;
;                 if (g < M) {
;                     const int b = g >= T ? 1 : 0, t = g - b * T;
;                     const float* sp = t < 16 ? srcm + (size_t)(b * 16 + t) * DM : srcx + ((size_t)b * SEQ + (t - 16)) * DM;
;                     float* dp = t < 16 ? (dstm ? dstm + (size_t)(b * 16 + t) * DM : (float*)nullptr) : dstx + ((size_t)b * SEQ + (t - 16)) * DM;
;                     const int col0 = u.pn * BM + wc * 32 + 8 * fq;
; #pragma unroll
;                     for (int bj = 0; bj < 2; ++bj) {
;                         const int col = col0 + bj * HALF;
;                         const f32x4 v0 = *(const f32x4*)(sp + col) + acc[ai][bj][m][0], v1 = *(const f32x4*)(sp + col + 4) + acc[ai][bj][m][1];
;                         if (dp) { *(f32x4*)(dp + col) = v0; *(f32x4*)(dp + col + 4) = v1; }
;                         if (hb) { u32x4 w; w.x = cvt_pk_bf16(v0[0], v0[1]); w.y = cvt_pk_bf16(v0[2], v0[3]); w.z = cvt_pk_bf16(v1[0], v1[1]); w.w = cvt_pk_bf16(v1[2], v1[3]); *(u32x4*)(hb + (size_t)g * DM + col) = w; }
;                         ss += (v0[0] * v0[0] + v0[1] * v0[1]) + (v0[2] * v0[2] + v0[3] * v0[3]) + (v1[0] * v1[0] + v1[1] * v1[1]) + (v1[2] * v1[2] + v1[3] * v1[3]);
.LBB0_2048:
	v_lshl_add_u32 v148, s0, 8, v160
	v_lshl_or_b32 v146, s12, 8, v162
	v_cmp_gt_i32_e32 vcc, s56, v148
	v_mov_b32_e32 v136, 0
	s_and_saveexec_b64 s[30:31], vcc
	s_cbranch_execz .LBB0_2062
	v_mov_b32_e32 v226, v146
	v_mov_b32_e32 v227, 0
	v_mov_b32_e32 v220, v148
	v_add_u32_e32 v221, 0x3ff0, v220
	v_lshrrev_b32_e32 v221, 15, v221
	v_mul_u32_u24_e32 v224, 0x4010, v221
	v_sub_u32_e32 v224, v220, v224
	v_lshlrev_b32_e32 v225, 4, v221
	v_cmp_gt_u32_e64 s[12:13], 16, v224
	v_add_u32_e32 v224, v224, v225
	v_sub_u32_e32 v220, v220, v225
	v_subrev_u32_e32 v220, 16, v220
	v_mov_b32_e32 v222, s92
	v_mov_b32_e32 v223, s93
	v_cndmask_b32_e64 v220, v220, v224, s[12:13]
	v_mov_b32_e32 v224, s64
	v_mov_b32_e32 v225, s65
	v_cndmask_b32_e64 v222, v222, v224, s[12:13]
	v_cndmask_b32_e64 v223, v223, v225, s[12:13]
	v_mov_b32_e32 v221, 0
	v_lshlrev_b64 v[220:221], 13, v[220:221]
	v_lshl_add_u64 v[220:221], v[220:221], 0, v[222:223]
	v_lshl_add_u64 v[220:221], v[226:227], 2, v[220:221]
	global_load_dwordx4 v[172:175], v[220:221], off
	global_load_dwordx4 v[176:179], v[220:221], off offset:16
	global_load_dwordx4 v[180:183], v[220:221], off offset:512
	global_load_dwordx4 v[184:187], v[220:221], off offset:528
	v_add_u32_e32 v220, 16, v148
	v_add_u32_e32 v221, 0x3ff0, v220
	v_lshrrev_b32_e32 v221, 15, v221
	v_mul_u32_u24_e32 v224, 0x4010, v221
	v_sub_u32_e32 v224, v220, v224
	v_lshlrev_b32_e32 v225, 4, v221
	v_cmp_gt_u32_e64 s[12:13], 16, v224
	v_add_u32_e32 v224, v224, v225
	v_sub_u32_e32 v220, v220, v225
	v_subrev_u32_e32 v220, 16, v220
	v_mov_b32_e32 v222, s92
	v_mov_b32_e32 v223, s93
	v_cndmask_b32_e64 v220, v220, v224, s[12:13]
	v_mov_b32_e32 v224, s64
	v_mov_b32_e32 v225, s65
	v_cndmask_b32_e64 v222, v222, v224, s[12:13]
	v_cndmask_b32_e64 v223, v223, v225, s[12:13]
	v_mov_b32_e32 v221, 0
	v_lshlrev_b64 v[220:221], 13, v[220:221]
	v_lshl_add_u64 v[220:221], v[220:221], 0, v[222:223]
	v_lshl_add_u64 v[220:221], v[226:227], 2, v[220:221]
	global_load_dwordx4 v[188:191], v[220:221], off
	global_load_dwordx4 v[192:195], v[220:221], off offset:16
	global_load_dwordx4 v[196:199], v[220:221], off offset:512
	global_load_dwordx4 v[200:203], v[220:221], off offset:528
	v_add_u32_e32 v220, 32, v148
	v_add_u32_e32 v221, 0x3ff0, v220
	v_lshrrev_b32_e32 v221, 15, v221
	v_mul_u32_u24_e32 v224, 0x4010, v221
	v_sub_u32_e32 v224, v220, v224
	v_lshlrev_b32_e32 v225, 4, v221
	v_cmp_gt_u32_e64 s[12:13], 16, v224
	v_add_u32_e32 v224, v224, v225
	v_sub_u32_e32 v220, v220, v225
	v_subrev_u32_e32 v220, 16, v220
	v_mov_b32_e32 v222, s92
	v_mov_b32_e32 v223, s93
	v_cndmask_b32_e64 v220, v220, v224, s[12:13]
	v_mov_b32_e32 v224, s64
	v_mov_b32_e32 v225, s65
	v_cndmask_b32_e64 v222, v222, v224, s[12:13]
	v_cndmask_b32_e64 v223, v223, v225, s[12:13]
	v_mov_b32_e32 v221, 0
	v_lshlrev_b64 v[220:221], 13, v[220:221]
	v_lshl_add_u64 v[220:221], v[220:221], 0, v[222:223]
	v_lshl_add_u64 v[220:221], v[226:227], 2, v[220:221]
	global_load_dwordx4 v[204:207], v[220:221], off
	global_load_dwordx4 v[208:211], v[220:221], off offset:16
	global_load_dwordx4 v[212:215], v[220:221], off offset:512
	global_load_dwordx4 v[216:219], v[220:221], off offset:528
	v_cmp_lt_i32_e64 s[12:13], s57, v148
	s_nop 1
	v_cndmask_b32_e64 v136, 0, v166, s[12:13]
	v_add_u32_e32 v147, v136, v148
	v_cmp_lt_i32_e64 s[0:1], 15, v147
	v_cndmask_b32_e64 v149, 0, v167, s[12:13]
	s_and_saveexec_b64 s[34:35], s[0:1]
	s_xor_b64 s[34:35], exec, s[34:35]
	v_add3_u32 v136, v147, v149, -16
	v_mov_b64_e32 v[150:151], v[136:137]
	s_or_saveexec_b64 s[34:35], s[34:35]
	v_mov_b64_e32 v[152:153], s[92:93]
	v_cndmask_b32_e64 v136, 0, 16, s[12:13]
	s_xor_b64 exec, exec, s[34:35]
	v_add_u32_e32 v150, v147, v136
	v_ashrrev_i32_e32 v151, 31, v150
	v_mov_b64_e32 v[152:153], s[64:65]
	s_or_b64 exec, exec, s[34:35]
	s_and_saveexec_b64 s[12:13], s[0:1]
	s_xor_b64 s[0:1], exec, s[12:13]
	s_cbranch_execz .LBB0_2055
	v_add3_u32 v136, v147, v149, -16
	v_mov_b64_e32 v[156:157], v[136:137]
	s_or_saveexec_b64 s[0:1], s[0:1]
	v_mov_b64_e32 v[158:159], s[92:93]
	s_xor_b64 exec, exec, s[0:1]
	s_cbranch_execnz .LBB0_2056
	s_branch .LBB0_2057

;     __device__ __forceinline__ void operator()(f32x4 (&acc)[2][2][4][2], const Unit& u, int wr, int wc, int fr_in, int fq_in) const {
;     ...
;         const int b = u.pm / 65, jt = u.pm % 65, tb = jt * 254 - 1;
; #pragma unroll
;         for (int ai = 0; ai < 2; ++ai)
; #pragma unroll
;             for (int m = 0; m < 4; ++m) {
;                 const int t = tb + ai * HALF + wr * 64 + m * 16 + fr; const bool ok = (t >= 0) && (t < T);
;                 const float rs = ok ? rsqrtf(ssq[b * T + (ok ? t : 0)] * (1.0f / DM) + EPS) : 0.f;
; #pragma unroll
;                 for (int bj = 0; bj < 2; ++bj)
; #pragma unroll
;                     for (int n = 0; n < 2; ++n)
; #pragma unroll
;                         for (int e = 0; e < 4; ++e) acc[ai][bj][m][n][e] = acc[ai][bj][m][n][e] * rs;
;             }
.LBB0_2248:
	s_mul_hi_i32 s0, s33, 0x7e07e07f
	s_lshr_b32 s1, s0, 31
	s_ashr_i32 s0, s0, 5
	s_add_i32 s31, s0, s1
	s_mul_i32 s0, s31, 0x41
	s_sub_i32 s80, s33, s0
	s_mulk_i32 s80, 0xfe
	s_add_i32 s33, s80, -1
	v_mbcnt_lo_u32_b32 v145, -1, 0
	v_mbcnt_hi_u32_b32 v145, -1, v145
	s_add_i32 s0, s33, s53
	v_and_b32_e32 v181, 15, v145
	v_add_u32_e32 v146, s0, v181
	s_mulk_i32 s31, 0x4010
	v_add_u32_e32 v232, s31, v146
	v_ashrrev_i32_e32 v233, 31, v232
	v_lshl_add_u64 v[232:233], v[232:233], 2, s[14:15]
	global_load_dword v224, v[232:233], off
	global_load_dword v225, v[232:233], off offset:64
	global_load_dword v226, v[232:233], off offset:128
	global_load_dword v227, v[232:233], off offset:192
	global_load_dword v228, v[232:233], off offset:512
	global_load_dword v229, v[232:233], off offset:576
	global_load_dword v230, v[232:233], off offset:640
	global_load_dword v231, v[232:233], off offset:704
	s_waitcnt vmcnt(0)
	v_cmp_gt_u32_e32 vcc, s51, v146
	v_mov_b32_e32 v162, 0
	v_mov_b32_e32 v202, 0
	s_and_saveexec_b64 s[0:1], vcc
	s_cbranch_execz .LBB0_2250
	v_add_u32_e32 v148, s31, v146
	v_ashrrev_i32_e32 v149, 31, v148
	v_lshl_add_u64 v[148:149], v[148:149], 2, s[14:15]
	v_mov_b32_e32 v144, v224
	v_fmamk_f32 v144, v144, 0x3a000000, v251
	v_mul_f32_e32 v147, 0x4b800000, v144
	v_cmp_gt_f32_e32 vcc, s75, v144
	s_nop 1
	v_cndmask_b32_e32 v144, v144, v147, vcc
	v_rsq_f32_e32 v144, v144
	s_nop 0
	v_mul_f32_e32 v147, 0x45800000, v144
	v_cndmask_b32_e32 v202, v144, v147, vcc
.LBB0_2250:
	s_or_b64 exec, exec, s[0:1]
	v_add_u32_e32 v144, 16, v146
	v_cmp_gt_u32_e32 vcc, s51, v144
	s_and_saveexec_b64 s[0:1], vcc
	s_cbranch_execz .LBB0_2252
	v_add_u32_e32 v148, s31, v144
	v_ashrrev_i32_e32 v149, 31, v148
	v_lshl_add_u64 v[148:149], v[148:149], 2, s[14:15]
	v_mov_b32_e32 v144, v225
	v_fmamk_f32 v144, v144, 0x3a000000, v251
	v_mul_f32_e32 v147, 0x4b800000, v144
	v_cmp_gt_f32_e32 vcc, s75, v144
	s_nop 1
	v_cndmask_b32_e32 v144, v144, v147, vcc
	v_rsq_f32_e32 v144, v144
	s_nop 0
	v_mul_f32_e32 v147, 0x45800000, v144
	v_cndmask_b32_e32 v162, v144, v147, vcc
.LBB0_2252:
	s_or_b64 exec, exec, s[0:1]
	v_add_u32_e32 v144, 32, v146
	v_cmp_gt_u32_e32 vcc, s51, v144
	v_mov_b32_e32 v186, 0
	v_mov_b32_e32 v198, 0
	s_and_saveexec_b64 s[0:1], vcc
	s_cbranch_execz .LBB0_2254
	v_add_u32_e32 v148, s31, v144
	v_ashrrev_i32_e32 v149, 31, v148
	v_lshl_add_u64 v[148:149], v[148:149], 2, s[14:15]
	v_mov_b32_e32 v144, v226
	v_fmamk_f32 v144, v144, 0x3a000000, v251
	v_mul_f32_e32 v147, 0x4b800000, v144
	v_cmp_gt_f32_e32 vcc, s75, v144
	s_nop 1
	v_cndmask_b32_e32 v144, v144, v147, vcc
	v_rsq_f32_e32 v144, v144
	s_nop 0
	v_mul_f32_e32 v147, 0x45800000, v144
	v_cndmask_b32_e32 v198, v144, v147, vcc
.LBB0_2254:
	s_or_b64 exec, exec, s[0:1]
	v_add_u32_e32 v144, 48, v146
	v_cmp_gt_u32_e32 vcc, s51, v144
	s_and_saveexec_b64 s[0:1], vcc
	s_cbranch_execz .LBB0_2256
	v_add_u32_e32 v148, s31, v144
	v_ashrrev_i32_e32 v149, 31, v148
	v_lshl_add_u64 v[148:149], v[148:149], 2, s[14:15]
	v_mov_b32_e32 v144, v227
	v_fmamk_f32 v144, v144, 0x3a000000, v251
	v_mul_f32_e32 v147, 0x4b800000, v144
	v_cmp_gt_f32_e32 vcc, s75, v144
	s_nop 1
	v_cndmask_b32_e32 v144, v144, v147, vcc
	v_rsq_f32_e32 v144, v144
	s_nop 0
	v_mul_f32_e32 v147, 0x45800000, v144
	v_cndmask_b32_e32 v186, v144, v147, vcc
.LBB0_2256:
	s_or_b64 exec, exec, s[0:1]
	v_add_u32_e32 v144, 0x80, v146
	v_cmp_gt_u32_e32 vcc, s51, v144
	v_mov_b32_e32 v180, 0
	v_mov_b32_e32 v164, 0
	s_and_saveexec_b64 s[0:1], vcc
	s_cbranch_execz .LBB0_2258
	v_add_u32_e32 v148, s31, v144
	v_ashrrev_i32_e32 v149, 31, v148
	v_lshl_add_u64 v[148:149], v[148:149], 2, s[14:15]
	v_mov_b32_e32 v144, v228
	v_fmamk_f32 v144, v144, 0x3a000000, v251
	v_mul_f32_e32 v147, 0x4b800000, v144
	v_cmp_gt_f32_e32 vcc, s75, v144
	s_nop 1
	v_cndmask_b32_e32 v144, v144, v147, vcc
	v_rsq_f32_e32 v144, v144
	s_nop 0
	v_mul_f32_e32 v147, 0x45800000, v144
	v_cndmask_b32_e32 v164, v144, v147, vcc
.LBB0_2258:
	s_or_b64 exec, exec, s[0:1]
	v_add_u32_e32 v144, 0x90, v146
	v_cmp_gt_u32_e32 vcc, s51, v144
	s_and_saveexec_b64 s[0:1], vcc
	s_cbranch_execz .LBB0_2260
	v_add_u32_e32 v148, s31, v144
	v_ashrrev_i32_e32 v149, 31, v148
	v_lshl_add_u64 v[148:149], v[148:149], 2, s[14:15]
	v_mov_b32_e32 v144, v229
	v_fmamk_f32 v144, v144, 0x3a000000, v251
	v_mul_f32_e32 v147, 0x4b800000, v144
	v_cmp_gt_f32_e32 vcc, s75, v144
	s_nop 1
	v_cndmask_b32_e32 v144, v144, v147, vcc
	v_rsq_f32_e32 v144, v144
	s_nop 0
	v_mul_f32_e32 v147, 0x45800000, v144
	v_cndmask_b32_e32 v180, v144, v147, vcc
.LBB0_2260:
	s_or_b64 exec, exec, s[0:1]
	v_add_u32_e32 v147, 0xa0, v146
	v_cmp_gt_u32_e32 vcc, s51, v147
	v_mov_b32_e32 v144, 0
	v_mov_b32_e32 v160, 0
	s_and_saveexec_b64 s[0:1], vcc
	s_cbranch_execz .LBB0_2262
	v_add_u32_e32 v148, s31, v147
	v_ashrrev_i32_e32 v149, 31, v148
	v_lshl_add_u64 v[148:149], v[148:149], 2, s[14:15]
	v_mov_b32_e32 v147, v230
	v_fmamk_f32 v147, v147, 0x3a000000, v251
	v_mul_f32_e32 v148, 0x4b800000, v147
	v_cmp_gt_f32_e32 vcc, s75, v147
	s_nop 1
	v_cndmask_b32_e32 v147, v147, v148, vcc
	v_rsq_f32_e32 v147, v147
	s_nop 0
	v_mul_f32_e32 v148, 0x45800000, v147
	v_cndmask_b32_e32 v160, v147, v148, vcc
.LBB0_2262:
	s_or_b64 exec, exec, s[0:1]
	v_add_u32_e32 v146, 0xb0, v146
	v_cmp_gt_u32_e32 vcc, s51, v146
	s_and_saveexec_b64 s[0:1], vcc
	s_cbranch_execz .LBB0_2264
	v_add_u32_e32 v146, s31, v146
	v_ashrrev_i32_e32 v147, 31, v146
	v_lshl_add_u64 v[146:147], v[146:147], 2, s[14:15]
	v_mov_b32_e32 v144, v231
	v_fmamk_f32 v144, v144, 0x3a000000, v251
	v_mul_f32_e32 v146, 0x4b800000, v144
	v_cmp_gt_f32_e32 vcc, s75, v144
	s_nop 1
	v_cndmask_b32_e32 v144, v144, v146, vcc
	v_rsq_f32_e32 v144, v144
	s_nop 0
	v_mul_f32_e32 v146, 0x45800000, v144
	v_cndmask_b32_e32 v144, v144, v146, vcc
